# RESIDN epilogues A/B/C: all 4 gate loads (as 8 dwordx2 into the product registers) issued up front, base loads issued before waiting, gate products computed in place after vmcnt(16)/(8)
# speedup vs baseline: 1.0010x; 1.0010x over previous
.LBB0_458:
	s_lshl_b32 s0, s52, 8
	v_mov_b32_e32 v254, v249
	v_mov_b32_e32 v250, v243
	s_or_b32 s0, s0, s31
	s_lshl_b32 s83, s40, 8
	v_lshl_add_u32 v216, v254, 3, s0
	s_ashr_i32 s0, s40, 5
	s_mul_hi_i32 s1, s0, 0x9000
	s_mul_i32 s0, s0, 0x9000
	s_add_u32 s0, s20, s0
	s_addc_u32 s1, s21, s1
	v_ashrrev_i32_e32 v217, 31, v216
	v_lshl_add_u64 v[138:139], v[216:217], 2, s[0:1]
	global_load_dwordx2 v[232:233], v[138:139], off offset:16
	global_load_dwordx2 v[230:231], v[138:139], off offset:24
	global_load_dwordx2 v[240:241], v[138:139], off
	global_load_dwordx2 v[238:239], v[138:139], off offset:8
	global_load_dwordx2 v[228:229], v[138:139], off offset:528
	global_load_dwordx2 v[226:227], v[138:139], off offset:536
	global_load_dwordx2 v[236:237], v[138:139], off offset:512
	global_load_dwordx2 v[234:235], v[138:139], off offset:520
	s_mov_b32 s25, s24
	v_add_u32_e32 v253, s30, v250
	v_add_u32_e32 v220, s83, v253
	v_ashrrev_i32_e32 v221, 31, v220
	v_add_u32_e32 v218, 16, v220
	v_ashrrev_i32_e32 v219, 31, v218
	v_add_u32_e32 v214, 32, v220
	v_ashrrev_i32_e32 v215, 31, v214
	v_add_u32_e32 v212, 48, v220
	v_ashrrev_i32_e32 v213, 31, v212
	v_add_u32_e32 v210, 0x80, v220
	v_ashrrev_i32_e32 v211, 31, v210
	v_add_u32_e32 v208, 0x90, v220
	v_ashrrev_i32_e32 v209, 31, v208
	v_add_u32_e32 v206, 0xa0, v220
	v_add_u32_e32 v204, 0xb0, v220
	v_ashrrev_i32_e32 v207, 31, v206
	v_ashrrev_i32_e32 v205, 31, v204
	v_cmp_eq_u32_e32 vcc, 0, v254
	v_readlane_b32 s0, v255, 19
	v_readlane_b32 s1, v255, 20
	v_lshlrev_b64 v[122:123], 11, v[220:221]
	v_lshl_add_u64 v[126:127], v[216:217], 1, s[0:1]
	v_lshl_add_u64 v[122:123], v[126:127], 0, v[122:123]
	global_load_dwordx4 v[190:193], v[122:123], off
	global_load_dwordx4 v[186:189], v[122:123], off offset:256
	v_lshlrev_b64 v[122:123], 11, v[218:219]
	v_lshl_add_u64 v[122:123], v[126:127], 0, v[122:123]
	global_load_dwordx4 v[182:185], v[122:123], off
	global_load_dwordx4 v[178:181], v[122:123], off offset:256
	v_lshlrev_b64 v[122:123], 11, v[214:215]
	v_lshl_add_u64 v[122:123], v[126:127], 0, v[122:123]
	global_load_dwordx4 v[174:177], v[122:123], off
	global_load_dwordx4 v[170:173], v[122:123], off offset:256
	v_lshlrev_b64 v[122:123], 11, v[212:213]
	v_lshl_add_u64 v[122:123], v[126:127], 0, v[122:123]
	global_load_dwordx4 v[166:169], v[122:123], off
	global_load_dwordx4 v[162:165], v[122:123], off offset:256
	v_lshlrev_b64 v[122:123], 11, v[210:211]
	v_lshl_add_u64 v[122:123], v[126:127], 0, v[122:123]
	global_load_dwordx4 v[158:161], v[122:123], off
	global_load_dwordx4 v[154:157], v[122:123], off offset:256
	v_lshlrev_b64 v[122:123], 11, v[208:209]
	v_lshl_add_u64 v[122:123], v[126:127], 0, v[122:123]
	global_load_dwordx4 v[150:153], v[122:123], off
	global_load_dwordx4 v[146:149], v[122:123], off offset:256
	v_lshlrev_b64 v[122:123], 11, v[206:207]
	v_lshlrev_b64 v[128:129], 11, v[204:205]
	v_lshl_add_u64 v[122:123], v[126:127], 0, v[122:123]
	v_lshl_add_u64 v[126:127], v[126:127], 0, v[128:129]
	global_load_dwordx4 v[138:141], v[122:123], off
	s_nop 0
	global_load_dwordx4 v[122:125], v[122:123], off offset:256
	s_nop 0
	global_load_dwordx4 v[142:145], v[126:127], off
	s_nop 0
	global_load_dwordx4 v[126:129], v[126:127], off offset:256
	v_readlane_b32 s0, v255, 42
	v_readlane_b32 s1, v255, 43
	s_waitcnt vmcnt(16)
	v_pk_mul_f32 v[230:231], s[24:25], v[230:231]
	v_pk_mul_f32 v[238:239], v[238:239], s[24:25]
	v_pk_mul_f32 v[240:241], v[240:241], s[0:1]
	v_pk_mul_f32 v[232:233], s[0:1], v[232:233]
	v_pk_mul_f32 v[228:229], s[0:1], v[228:229]
	v_pk_mul_f32 v[236:237], s[0:1], v[236:237]
	v_pk_mul_f32 v[234:235], s[24:25], v[234:235]
	v_pk_mul_f32 v[226:227], s[24:25], v[226:227]
	s_waitcnt vmcnt(15)
	v_cvt_f32_f16_e32 v222, v190
	v_cvt_f32_f16_sdwa v223, v190 dst_sel:DWORD dst_unused:UNUSED_PAD src0_sel:WORD_1
	v_cvt_f32_f16_e32 v190, v191
	v_cvt_f32_f16_sdwa v191, v191 dst_sel:DWORD dst_unused:UNUSED_PAD src0_sel:WORD_1
	v_pk_fma_f32 v[134:135], v[134:135], v[240:241], v[222:223]
	v_pk_fma_f32 v[136:137], v[136:137], v[238:239], v[190:191]
	v_cvt_f32_f16_e32 v190, v192
	v_cvt_f32_f16_sdwa v191, v192 dst_sel:DWORD dst_unused:UNUSED_PAD src0_sel:WORD_1
	v_cvt_f32_f16_e32 v192, v193
	v_cvt_f32_f16_sdwa v193, v193 dst_sel:DWORD dst_unused:UNUSED_PAD src0_sel:WORD_1
	v_pk_fma_f32 v[130:131], v[130:131], v[232:233], v[190:191]
	s_waitcnt vmcnt(14)
	v_cvt_f32_f16_e32 v190, v186
	v_cvt_f32_f16_sdwa v191, v186 dst_sel:DWORD dst_unused:UNUSED_PAD src0_sel:WORD_1
	v_cvt_f32_f16_e32 v186, v187
	v_cvt_f32_f16_sdwa v187, v187 dst_sel:DWORD dst_unused:UNUSED_PAD src0_sel:WORD_1
	v_pk_fma_f32 v[132:133], v[132:133], v[230:231], v[192:193]
	v_pk_fma_f32 v[118:119], v[118:119], v[236:237], v[190:191]
	v_pk_fma_f32 v[120:121], v[120:121], v[234:235], v[186:187]
	v_cvt_f32_f16_e32 v186, v188
	v_cvt_f32_f16_sdwa v187, v188 dst_sel:DWORD dst_unused:UNUSED_PAD src0_sel:WORD_1
	v_cvt_f32_f16_e32 v188, v189
	v_cvt_f32_f16_sdwa v189, v189 dst_sel:DWORD dst_unused:UNUSED_PAD src0_sel:WORD_1
	v_pk_fma_f32 v[114:115], v[114:115], v[228:229], v[186:187]
	v_mul_f32_e32 v186, v135, v135
	v_mul_f32_e32 v187, v137, v137
	v_fmac_f32_e32 v186, v134, v134
	v_fmac_f32_e32 v187, v136, v136
	v_pk_fma_f32 v[116:117], v[116:117], v[226:227], v[188:189]
	v_add_f32_e32 v186, v186, v187
	v_mul_f32_e32 v187, v131, v131
	v_mul_f32_e32 v188, v133, v133
	v_fmac_f32_e32 v187, v130, v130
	v_fmac_f32_e32 v188, v132, v132
	v_add_f32_e32 v187, v187, v188
	v_add_f32_e32 v186, v186, v187
	v_mul_f32_e32 v187, v119, v119
	v_mul_f32_e32 v188, v121, v121
	v_fmac_f32_e32 v187, v118, v118
	v_fmac_f32_e32 v188, v120, v120
	v_add_f32_e32 v187, v187, v188
	v_add_f32_e32 v186, v186, v187
	v_mul_f32_e32 v187, v115, v115
	v_mul_f32_e32 v188, v117, v117
	v_fmac_f32_e32 v187, v114, v114
	v_fmac_f32_e32 v188, v116, v116
	v_add_f32_e32 v187, v187, v188
	v_add_f32_e32 v186, v187, v186
	ds_swizzle_b32 v187, v186 offset:swizzle(SWAP,16)
	s_waitcnt lgkmcnt(0)
	v_add_f32_e32 v187, v186, v187
	v_mov_b32_e32 v188, v187
	s_nop 1
	v_permlane32_swap_b32_e32 v187, v188
	v_lshl_add_u32 v186, v250, 4, s74
	s_and_saveexec_b64 s[0:1], vcc
	v_add_f32_e32 v187, v187, v188
	ds_write_b32 v186, v187
	s_or_b64 exec, exec, s[0:1]
	s_waitcnt vmcnt(13)
	v_cvt_f32_f16_sdwa v189, v182 dst_sel:DWORD dst_unused:UNUSED_PAD src0_sel:WORD_1
	v_cvt_f32_f16_e32 v188, v182
	v_cvt_f32_f16_sdwa v191, v183 dst_sel:DWORD dst_unused:UNUSED_PAD src0_sel:WORD_1
	v_cvt_f32_f16_e32 v190, v183
	v_cvt_f32_f16_sdwa v183, v184 dst_sel:DWORD dst_unused:UNUSED_PAD src0_sel:WORD_1
	v_cvt_f32_f16_e32 v182, v184
	v_pk_fma_f32 v[110:111], v[110:111], v[240:241], v[188:189]
	v_cvt_f32_f16_sdwa v189, v185 dst_sel:DWORD dst_unused:UNUSED_PAD src0_sel:WORD_1
	v_cvt_f32_f16_e32 v188, v185
	v_pk_fma_f32 v[106:107], v[106:107], v[232:233], v[182:183]
	s_waitcnt vmcnt(12)
	v_cvt_f32_f16_sdwa v183, v178 dst_sel:DWORD dst_unused:UNUSED_PAD src0_sel:WORD_1
	v_cvt_f32_f16_e32 v182, v178
	v_cvt_f32_f16_sdwa v185, v179 dst_sel:DWORD dst_unused:UNUSED_PAD src0_sel:WORD_1
	v_cvt_f32_f16_e32 v184, v179
	v_cvt_f32_f16_sdwa v179, v180 dst_sel:DWORD dst_unused:UNUSED_PAD src0_sel:WORD_1
	v_cvt_f32_f16_e32 v178, v180
	v_pk_fma_f32 v[112:113], v[112:113], v[238:239], v[190:191]
	v_pk_fma_f32 v[108:109], v[108:109], v[230:231], v[188:189]
	v_pk_fma_f32 v[102:103], v[102:103], v[236:237], v[182:183]
	v_pk_fma_f32 v[98:99], v[98:99], v[228:229], v[178:179]
	v_mul_f32_e32 v178, v111, v111
	v_mul_f32_e32 v179, v113, v113
	v_fmac_f32_e32 v178, v110, v110
	v_fmac_f32_e32 v179, v112, v112
	v_add_f32_e32 v178, v178, v179
	v_mul_f32_e32 v179, v107, v107
	v_mul_f32_e32 v180, v109, v109
	v_cvt_f32_f16_sdwa v183, v181 dst_sel:DWORD dst_unused:UNUSED_PAD src0_sel:WORD_1
	v_cvt_f32_f16_e32 v182, v181
	v_fmac_f32_e32 v179, v106, v106
	v_fmac_f32_e32 v180, v108, v108
	v_pk_fma_f32 v[104:105], v[104:105], v[234:235], v[184:185]
	v_add_f32_e32 v179, v179, v180
	v_add_f32_e32 v178, v178, v179
	v_mul_f32_e32 v179, v103, v103
	v_mul_f32_e32 v180, v105, v105
	v_fmac_f32_e32 v179, v102, v102
	v_fmac_f32_e32 v180, v104, v104
	v_pk_fma_f32 v[100:101], v[100:101], v[226:227], v[182:183]
	v_add_f32_e32 v179, v179, v180
	v_add_f32_e32 v178, v178, v179
	v_mul_f32_e32 v179, v99, v99
	v_mul_f32_e32 v180, v101, v101
	v_fmac_f32_e32 v179, v98, v98
	v_fmac_f32_e32 v180, v100, v100
	v_add_f32_e32 v179, v179, v180
	v_add_f32_e32 v178, v179, v178
	ds_swizzle_b32 v179, v178 offset:swizzle(SWAP,16)
	s_waitcnt lgkmcnt(0)
	v_add_f32_e32 v178, v178, v179
	v_mov_b32_e32 v179, v178
	s_nop 1
	v_permlane32_swap_b32_e32 v178, v179
	s_and_saveexec_b64 s[0:1], vcc
	v_add_f32_e32 v178, v178, v179
	ds_write_b32 v186, v178 offset:256
	s_or_b64 exec, exec, s[0:1]
	s_waitcnt vmcnt(11)
	v_cvt_f32_f16_sdwa v179, v174 dst_sel:DWORD dst_unused:UNUSED_PAD src0_sel:WORD_1
	v_cvt_f32_f16_e32 v178, v174
	v_cvt_f32_f16_sdwa v181, v175 dst_sel:DWORD dst_unused:UNUSED_PAD src0_sel:WORD_1
	v_cvt_f32_f16_e32 v180, v175
	v_cvt_f32_f16_sdwa v175, v176 dst_sel:DWORD dst_unused:UNUSED_PAD src0_sel:WORD_1
	v_cvt_f32_f16_e32 v174, v176
	v_pk_fma_f32 v[94:95], v[94:95], v[240:241], v[178:179]
	v_cvt_f32_f16_sdwa v179, v177 dst_sel:DWORD dst_unused:UNUSED_PAD src0_sel:WORD_1
	v_cvt_f32_f16_e32 v178, v177
	v_pk_fma_f32 v[90:91], v[90:91], v[232:233], v[174:175]
	s_waitcnt vmcnt(10)
	v_cvt_f32_f16_sdwa v175, v170 dst_sel:DWORD dst_unused:UNUSED_PAD src0_sel:WORD_1
	v_cvt_f32_f16_e32 v174, v170
	v_cvt_f32_f16_sdwa v177, v171 dst_sel:DWORD dst_unused:UNUSED_PAD src0_sel:WORD_1
	v_cvt_f32_f16_e32 v176, v171
	v_cvt_f32_f16_sdwa v171, v172 dst_sel:DWORD dst_unused:UNUSED_PAD src0_sel:WORD_1
	v_cvt_f32_f16_e32 v170, v172
	v_pk_fma_f32 v[96:97], v[96:97], v[238:239], v[180:181]
	v_pk_fma_f32 v[92:93], v[92:93], v[230:231], v[178:179]
	v_pk_fma_f32 v[86:87], v[86:87], v[236:237], v[174:175]
	v_pk_fma_f32 v[82:83], v[82:83], v[228:229], v[170:171]
	v_mul_f32_e32 v170, v95, v95
	v_mul_f32_e32 v171, v97, v97
	v_fmac_f32_e32 v170, v94, v94
	v_fmac_f32_e32 v171, v96, v96
	v_add_f32_e32 v170, v170, v171
	v_mul_f32_e32 v171, v91, v91
	v_mul_f32_e32 v172, v93, v93
	v_cvt_f32_f16_sdwa v175, v173 dst_sel:DWORD dst_unused:UNUSED_PAD src0_sel:WORD_1
	v_cvt_f32_f16_e32 v174, v173
	v_fmac_f32_e32 v171, v90, v90
	v_fmac_f32_e32 v172, v92, v92
	v_pk_fma_f32 v[88:89], v[88:89], v[234:235], v[176:177]
	v_add_f32_e32 v171, v171, v172
	v_add_f32_e32 v170, v170, v171
	v_mul_f32_e32 v171, v87, v87
	v_mul_f32_e32 v172, v89, v89
	v_fmac_f32_e32 v171, v86, v86
	v_fmac_f32_e32 v172, v88, v88
	v_pk_fma_f32 v[84:85], v[84:85], v[226:227], v[174:175]
	v_add_f32_e32 v171, v171, v172
	v_add_f32_e32 v170, v170, v171
	v_mul_f32_e32 v171, v83, v83
	v_mul_f32_e32 v172, v85, v85
	v_fmac_f32_e32 v171, v82, v82
	v_fmac_f32_e32 v172, v84, v84
	v_add_f32_e32 v171, v171, v172
	v_add_f32_e32 v170, v171, v170
	ds_swizzle_b32 v171, v170 offset:swizzle(SWAP,16)
	s_waitcnt lgkmcnt(0)
	v_add_f32_e32 v170, v170, v171
	v_mov_b32_e32 v171, v170
	s_nop 1
	v_permlane32_swap_b32_e32 v170, v171
	s_and_saveexec_b64 s[0:1], vcc
	v_add_f32_e32 v170, v170, v171
	ds_write_b32 v186, v170 offset:512
	s_or_b64 exec, exec, s[0:1]
	s_waitcnt vmcnt(9)
	v_cvt_f32_f16_sdwa v171, v166 dst_sel:DWORD dst_unused:UNUSED_PAD src0_sel:WORD_1
	v_cvt_f32_f16_e32 v170, v166
	v_cvt_f32_f16_sdwa v173, v167 dst_sel:DWORD dst_unused:UNUSED_PAD src0_sel:WORD_1
	v_cvt_f32_f16_e32 v172, v167
	v_cvt_f32_f16_sdwa v167, v168 dst_sel:DWORD dst_unused:UNUSED_PAD src0_sel:WORD_1
	v_cvt_f32_f16_e32 v166, v168
	v_pk_fma_f32 v[78:79], v[78:79], v[240:241], v[170:171]
	v_cvt_f32_f16_sdwa v171, v169 dst_sel:DWORD dst_unused:UNUSED_PAD src0_sel:WORD_1
	v_cvt_f32_f16_e32 v170, v169
	v_pk_fma_f32 v[74:75], v[74:75], v[232:233], v[166:167]
	s_waitcnt vmcnt(8)
	v_cvt_f32_f16_sdwa v167, v162 dst_sel:DWORD dst_unused:UNUSED_PAD src0_sel:WORD_1
	v_cvt_f32_f16_e32 v166, v162
	v_cvt_f32_f16_sdwa v169, v163 dst_sel:DWORD dst_unused:UNUSED_PAD src0_sel:WORD_1
	v_cvt_f32_f16_e32 v168, v163
	v_cvt_f32_f16_sdwa v163, v164 dst_sel:DWORD dst_unused:UNUSED_PAD src0_sel:WORD_1
	v_cvt_f32_f16_e32 v162, v164
	v_pk_fma_f32 v[80:81], v[80:81], v[238:239], v[172:173]
	v_pk_fma_f32 v[76:77], v[76:77], v[230:231], v[170:171]
	v_pk_fma_f32 v[70:71], v[70:71], v[236:237], v[166:167]
	v_pk_fma_f32 v[66:67], v[66:67], v[228:229], v[162:163]
	v_mul_f32_e32 v162, v79, v79
	v_mul_f32_e32 v163, v81, v81
	v_fmac_f32_e32 v162, v78, v78
	v_fmac_f32_e32 v163, v80, v80
	v_add_f32_e32 v162, v162, v163
	v_mul_f32_e32 v163, v75, v75
	v_mul_f32_e32 v164, v77, v77
	v_cvt_f32_f16_sdwa v167, v165 dst_sel:DWORD dst_unused:UNUSED_PAD src0_sel:WORD_1
	v_cvt_f32_f16_e32 v166, v165
	v_fmac_f32_e32 v163, v74, v74
	v_fmac_f32_e32 v164, v76, v76
	v_pk_fma_f32 v[72:73], v[72:73], v[234:235], v[168:169]
	v_add_f32_e32 v163, v163, v164
	v_add_f32_e32 v162, v162, v163
	v_mul_f32_e32 v163, v71, v71
	v_mul_f32_e32 v164, v73, v73
	v_fmac_f32_e32 v163, v70, v70
	v_fmac_f32_e32 v164, v72, v72
	v_pk_fma_f32 v[68:69], v[68:69], v[226:227], v[166:167]
	v_add_f32_e32 v163, v163, v164
	v_add_f32_e32 v162, v162, v163
	v_mul_f32_e32 v163, v67, v67
	v_mul_f32_e32 v164, v69, v69
	v_fmac_f32_e32 v163, v66, v66
	v_fmac_f32_e32 v164, v68, v68
	v_add_f32_e32 v163, v163, v164
	v_add_f32_e32 v162, v163, v162
	ds_swizzle_b32 v163, v162 offset:swizzle(SWAP,16)
	s_waitcnt lgkmcnt(0)
	v_add_f32_e32 v162, v162, v163
	v_mov_b32_e32 v163, v162
	s_nop 1
	v_permlane32_swap_b32_e32 v162, v163
	s_and_saveexec_b64 s[0:1], vcc
	v_add_f32_e32 v162, v162, v163
	ds_write_b32 v186, v162 offset:768
	s_or_b64 exec, exec, s[0:1]
	s_waitcnt vmcnt(7)
	v_cvt_f32_f16_sdwa v163, v158 dst_sel:DWORD dst_unused:UNUSED_PAD src0_sel:WORD_1
	v_cvt_f32_f16_e32 v162, v158
	v_cvt_f32_f16_sdwa v165, v159 dst_sel:DWORD dst_unused:UNUSED_PAD src0_sel:WORD_1
	v_cvt_f32_f16_e32 v164, v159
	v_cvt_f32_f16_sdwa v159, v160 dst_sel:DWORD dst_unused:UNUSED_PAD src0_sel:WORD_1
	v_cvt_f32_f16_e32 v158, v160
	v_pk_fma_f32 v[62:63], v[62:63], v[240:241], v[162:163]
	v_cvt_f32_f16_sdwa v163, v161 dst_sel:DWORD dst_unused:UNUSED_PAD src0_sel:WORD_1
	v_cvt_f32_f16_e32 v162, v161
	v_pk_fma_f32 v[58:59], v[58:59], v[232:233], v[158:159]
	s_waitcnt vmcnt(6)
	v_cvt_f32_f16_sdwa v159, v154 dst_sel:DWORD dst_unused:UNUSED_PAD src0_sel:WORD_1
	v_cvt_f32_f16_e32 v158, v154
	v_cvt_f32_f16_sdwa v161, v155 dst_sel:DWORD dst_unused:UNUSED_PAD src0_sel:WORD_1
	v_cvt_f32_f16_e32 v160, v155
	v_cvt_f32_f16_sdwa v155, v156 dst_sel:DWORD dst_unused:UNUSED_PAD src0_sel:WORD_1
	v_cvt_f32_f16_e32 v154, v156
	v_pk_fma_f32 v[64:65], v[64:65], v[238:239], v[164:165]
	v_pk_fma_f32 v[60:61], v[60:61], v[230:231], v[162:163]
	v_pk_fma_f32 v[54:55], v[54:55], v[236:237], v[158:159]
	v_pk_fma_f32 v[50:51], v[50:51], v[228:229], v[154:155]
	v_mul_f32_e32 v154, v63, v63
	v_mul_f32_e32 v155, v65, v65
	v_fmac_f32_e32 v154, v62, v62
	v_fmac_f32_e32 v155, v64, v64
	v_add_f32_e32 v154, v154, v155
	v_mul_f32_e32 v155, v59, v59
	v_mul_f32_e32 v156, v61, v61
	v_cvt_f32_f16_sdwa v159, v157 dst_sel:DWORD dst_unused:UNUSED_PAD src0_sel:WORD_1
	v_cvt_f32_f16_e32 v158, v157
	v_fmac_f32_e32 v155, v58, v58
	v_fmac_f32_e32 v156, v60, v60
	v_pk_fma_f32 v[56:57], v[56:57], v[234:235], v[160:161]
	v_add_f32_e32 v155, v155, v156
	v_add_f32_e32 v154, v154, v155
	v_mul_f32_e32 v155, v55, v55
	v_mul_f32_e32 v156, v57, v57
	v_fmac_f32_e32 v155, v54, v54
	v_fmac_f32_e32 v156, v56, v56
	v_pk_fma_f32 v[52:53], v[52:53], v[226:227], v[158:159]
	v_add_f32_e32 v155, v155, v156
	v_add_f32_e32 v154, v154, v155
	v_mul_f32_e32 v155, v51, v51
	v_mul_f32_e32 v156, v53, v53
	v_fmac_f32_e32 v155, v50, v50
	v_fmac_f32_e32 v156, v52, v52
	v_add_f32_e32 v155, v155, v156
	v_add_f32_e32 v154, v155, v154
	ds_swizzle_b32 v155, v154 offset:swizzle(SWAP,16)
	s_waitcnt lgkmcnt(0)
	v_add_f32_e32 v154, v154, v155
	v_mov_b32_e32 v155, v154
	s_nop 1
	v_permlane32_swap_b32_e32 v154, v155
	s_and_saveexec_b64 s[0:1], vcc
	v_add_f32_e32 v154, v154, v155
	ds_write_b32 v186, v154 offset:2048
	s_or_b64 exec, exec, s[0:1]
	s_waitcnt vmcnt(5)
	v_cvt_f32_f16_sdwa v155, v150 dst_sel:DWORD dst_unused:UNUSED_PAD src0_sel:WORD_1
	v_cvt_f32_f16_e32 v154, v150
	v_cvt_f32_f16_sdwa v157, v151 dst_sel:DWORD dst_unused:UNUSED_PAD src0_sel:WORD_1
	v_cvt_f32_f16_e32 v156, v151
	v_cvt_f32_f16_sdwa v151, v152 dst_sel:DWORD dst_unused:UNUSED_PAD src0_sel:WORD_1
	v_cvt_f32_f16_e32 v150, v152
	v_pk_fma_f32 v[46:47], v[46:47], v[240:241], v[154:155]
	v_cvt_f32_f16_sdwa v155, v153 dst_sel:DWORD dst_unused:UNUSED_PAD src0_sel:WORD_1
	v_cvt_f32_f16_e32 v154, v153
	v_pk_fma_f32 v[42:43], v[42:43], v[232:233], v[150:151]
	s_waitcnt vmcnt(4)
	v_cvt_f32_f16_sdwa v151, v146 dst_sel:DWORD dst_unused:UNUSED_PAD src0_sel:WORD_1
	v_cvt_f32_f16_e32 v150, v146
	v_cvt_f32_f16_sdwa v153, v147 dst_sel:DWORD dst_unused:UNUSED_PAD src0_sel:WORD_1
	v_cvt_f32_f16_e32 v152, v147
	v_cvt_f32_f16_sdwa v147, v148 dst_sel:DWORD dst_unused:UNUSED_PAD src0_sel:WORD_1
	v_cvt_f32_f16_e32 v146, v148
	v_pk_fma_f32 v[48:49], v[48:49], v[238:239], v[156:157]
	v_pk_fma_f32 v[44:45], v[44:45], v[230:231], v[154:155]
	v_pk_fma_f32 v[38:39], v[38:39], v[236:237], v[150:151]
	v_pk_fma_f32 v[34:35], v[34:35], v[228:229], v[146:147]
	v_mul_f32_e32 v146, v47, v47
	v_mul_f32_e32 v147, v49, v49
	v_fmac_f32_e32 v146, v46, v46
	v_fmac_f32_e32 v147, v48, v48
	v_add_f32_e32 v146, v146, v147
	v_mul_f32_e32 v147, v43, v43
	v_mul_f32_e32 v148, v45, v45
	v_cvt_f32_f16_sdwa v151, v149 dst_sel:DWORD dst_unused:UNUSED_PAD src0_sel:WORD_1
	v_cvt_f32_f16_e32 v150, v149
	v_fmac_f32_e32 v147, v42, v42
	v_fmac_f32_e32 v148, v44, v44
	v_pk_fma_f32 v[40:41], v[40:41], v[234:235], v[152:153]
	v_add_f32_e32 v147, v147, v148
	v_add_f32_e32 v146, v146, v147
	v_mul_f32_e32 v147, v39, v39
	v_mul_f32_e32 v148, v41, v41
	v_fmac_f32_e32 v147, v38, v38
	v_fmac_f32_e32 v148, v40, v40
	v_pk_fma_f32 v[36:37], v[36:37], v[226:227], v[150:151]
	v_add_f32_e32 v147, v147, v148
	v_add_f32_e32 v146, v146, v147
	v_mul_f32_e32 v147, v35, v35
	v_mul_f32_e32 v148, v37, v37
	v_fmac_f32_e32 v147, v34, v34
	v_fmac_f32_e32 v148, v36, v36
	v_add_f32_e32 v147, v147, v148
	v_add_f32_e32 v146, v147, v146
	ds_swizzle_b32 v147, v146 offset:swizzle(SWAP,16)
	s_waitcnt lgkmcnt(0)
	v_add_f32_e32 v146, v146, v147
	v_mov_b32_e32 v147, v146
	s_nop 1
	v_permlane32_swap_b32_e32 v146, v147
	s_and_saveexec_b64 s[0:1], vcc
	v_add_f32_e32 v146, v146, v147
	ds_write_b32 v186, v146 offset:2304
	s_or_b64 exec, exec, s[0:1]
	s_waitcnt vmcnt(3)
	v_cvt_f32_f16_sdwa v147, v138 dst_sel:DWORD dst_unused:UNUSED_PAD src0_sel:WORD_1
	v_cvt_f32_f16_e32 v146, v138
	v_cvt_f32_f16_sdwa v149, v139 dst_sel:DWORD dst_unused:UNUSED_PAD src0_sel:WORD_1
	v_cvt_f32_f16_e32 v148, v139
	v_cvt_f32_f16_sdwa v139, v140 dst_sel:DWORD dst_unused:UNUSED_PAD src0_sel:WORD_1
	v_cvt_f32_f16_e32 v138, v140
	v_pk_fma_f32 v[30:31], v[30:31], v[240:241], v[146:147]
	v_cvt_f32_f16_sdwa v147, v141 dst_sel:DWORD dst_unused:UNUSED_PAD src0_sel:WORD_1
	v_cvt_f32_f16_e32 v146, v141
	v_pk_fma_f32 v[26:27], v[26:27], v[232:233], v[138:139]
	s_waitcnt vmcnt(2)
	v_cvt_f32_f16_sdwa v139, v122 dst_sel:DWORD dst_unused:UNUSED_PAD src0_sel:WORD_1
	v_cvt_f32_f16_e32 v138, v122
	v_cvt_f32_f16_sdwa v141, v123 dst_sel:DWORD dst_unused:UNUSED_PAD src0_sel:WORD_1
	v_cvt_f32_f16_e32 v140, v123
	v_cvt_f32_f16_sdwa v123, v124 dst_sel:DWORD dst_unused:UNUSED_PAD src0_sel:WORD_1
	v_cvt_f32_f16_e32 v122, v124
	v_pk_fma_f32 v[32:33], v[32:33], v[238:239], v[148:149]
	v_pk_fma_f32 v[28:29], v[28:29], v[230:231], v[146:147]
	v_pk_fma_f32 v[22:23], v[22:23], v[236:237], v[138:139]
	v_pk_fma_f32 v[18:19], v[18:19], v[228:229], v[122:123]
	v_mul_f32_e32 v122, v31, v31
	v_mul_f32_e32 v123, v33, v33
	v_fmac_f32_e32 v122, v30, v30
	v_fmac_f32_e32 v123, v32, v32
	v_add_f32_e32 v122, v122, v123
	v_mul_f32_e32 v123, v27, v27
	v_mul_f32_e32 v124, v29, v29
	v_cvt_f32_f16_sdwa v139, v125 dst_sel:DWORD dst_unused:UNUSED_PAD src0_sel:WORD_1
	v_cvt_f32_f16_e32 v138, v125
	v_fmac_f32_e32 v123, v26, v26
	v_fmac_f32_e32 v124, v28, v28
	v_pk_fma_f32 v[24:25], v[24:25], v[234:235], v[140:141]
	v_add_f32_e32 v123, v123, v124
	v_add_f32_e32 v122, v122, v123
	v_mul_f32_e32 v123, v23, v23
	v_mul_f32_e32 v124, v25, v25
	v_fmac_f32_e32 v123, v22, v22
	v_fmac_f32_e32 v124, v24, v24
	v_pk_fma_f32 v[20:21], v[20:21], v[226:227], v[138:139]
	v_add_f32_e32 v123, v123, v124
	v_add_f32_e32 v122, v122, v123
	v_mul_f32_e32 v123, v19, v19
	v_mul_f32_e32 v124, v21, v21
	v_fmac_f32_e32 v123, v18, v18
	v_fmac_f32_e32 v124, v20, v20
	v_add_f32_e32 v123, v123, v124
	v_add_f32_e32 v122, v123, v122
	ds_swizzle_b32 v123, v122 offset:swizzle(SWAP,16)
	s_waitcnt lgkmcnt(0)
	v_add_f32_e32 v122, v122, v123
	v_mov_b32_e32 v123, v122
	s_nop 1
	v_permlane32_swap_b32_e32 v122, v123
	s_and_saveexec_b64 s[0:1], vcc
	v_add_f32_e32 v122, v122, v123
	ds_write_b32 v186, v122 offset:2560
	s_or_b64 exec, exec, s[0:1]
	s_waitcnt vmcnt(1)
	v_cvt_f32_f16_sdwa v125, v142 dst_sel:DWORD dst_unused:UNUSED_PAD src0_sel:WORD_1
	v_cvt_f32_f16_e32 v124, v142
	v_cvt_f32_f16_sdwa v123, v143 dst_sel:DWORD dst_unused:UNUSED_PAD src0_sel:WORD_1
	v_cvt_f32_f16_e32 v122, v143
	v_pk_fma_f32 v[124:125], v[14:15], v[240:241], v[124:125]
	v_cvt_f32_f16_sdwa v15, v144 dst_sel:DWORD dst_unused:UNUSED_PAD src0_sel:WORD_1
	v_cvt_f32_f16_e32 v14, v144
	v_pk_fma_f32 v[122:123], v[16:17], v[238:239], v[122:123]
	v_cvt_f32_f16_sdwa v17, v145 dst_sel:DWORD dst_unused:UNUSED_PAD src0_sel:WORD_1
	v_cvt_f32_f16_e32 v16, v145
	v_pk_fma_f32 v[142:143], v[10:11], v[232:233], v[14:15]
	s_waitcnt vmcnt(0)
	v_cvt_f32_f16_sdwa v11, v126 dst_sel:DWORD dst_unused:UNUSED_PAD src0_sel:WORD_1
	v_cvt_f32_f16_e32 v10, v126
	v_pk_fma_f32 v[138:139], v[12:13], v[230:231], v[16:17]
	v_cvt_f32_f16_sdwa v13, v127 dst_sel:DWORD dst_unused:UNUSED_PAD src0_sel:WORD_1
	v_cvt_f32_f16_e32 v12, v127
	v_pk_fma_f32 v[140:141], v[6:7], v[236:237], v[10:11]
	v_cvt_f32_f16_sdwa v7, v128 dst_sel:DWORD dst_unused:UNUSED_PAD src0_sel:WORD_1
	v_cvt_f32_f16_e32 v6, v128
	v_pk_fma_f32 v[126:127], v[8:9], v[234:235], v[12:13]
	v_cvt_f32_f16_sdwa v9, v129 dst_sel:DWORD dst_unused:UNUSED_PAD src0_sel:WORD_1
	v_cvt_f32_f16_e32 v8, v129
	v_pk_fma_f32 v[144:145], v[2:3], v[228:229], v[6:7]
	v_mul_f32_e32 v2, v125, v125
	v_mul_f32_e32 v3, v123, v123
	v_fmac_f32_e32 v2, v124, v124
	v_fmac_f32_e32 v3, v122, v122
	v_pk_fma_f32 v[128:129], v[4:5], v[226:227], v[8:9]
	v_add_f32_e32 v2, v2, v3
	v_mul_f32_e32 v3, v143, v143
	v_mul_f32_e32 v4, v139, v139
	v_fmac_f32_e32 v3, v142, v142
	v_fmac_f32_e32 v4, v138, v138
	v_add_f32_e32 v3, v3, v4
	v_add_f32_e32 v2, v2, v3
	v_mul_f32_e32 v3, v141, v141
	v_mul_f32_e32 v4, v127, v127
	v_fmac_f32_e32 v3, v140, v140
	v_fmac_f32_e32 v4, v126, v126
	v_add_f32_e32 v3, v3, v4
	v_add_f32_e32 v2, v2, v3
	v_mul_f32_e32 v3, v145, v145
	v_mul_f32_e32 v4, v129, v129
	v_fmac_f32_e32 v3, v144, v144
	v_fmac_f32_e32 v4, v128, v128
	v_add_f32_e32 v3, v3, v4
	v_add_f32_e32 v2, v3, v2
	ds_swizzle_b32 v3, v2 offset:swizzle(SWAP,16)
	s_waitcnt lgkmcnt(0)
	v_add_f32_e32 v2, v2, v3
	v_mov_b32_e32 v3, v2
	s_nop 1
	v_permlane32_swap_b32_e32 v2, v3
	s_and_saveexec_b64 s[0:1], vcc
	v_add_f32_e32 v2, v2, v3
	ds_write_b32 v186, v2 offset:2816
	s_or_b64 exec, exec, s[0:1]
	s_waitcnt lgkmcnt(0)
	s_barrier
	v_lshl_add_u32 v3, v254, 4, v250
	v_cmp_gt_i32_e64 s[6:7], 32, v3
	v_and_or_b32 v2, v3, 31, s65
	s_and_saveexec_b64 s[0:1], s[6:7]
	s_cbranch_execz .LBB0_476
	v_lshl_add_u32 v4, v2, 4, 0
	v_add_u32_e32 v4, 0x20400, v4
	ds_read_b128 v[4:7], v4
	s_ashr_i32 s53, s52, 31
	s_waitcnt lgkmcnt(0)
	v_mov_b32_e32 v9, v6
	v_add_u32_e32 v6, s83, v2
	v_mov_b32_e32 v8, v5
	v_mov_b32_e32 v5, v7
	v_ashrrev_i32_e32 v7, 31, v6
	v_pk_add_f32 v[4:5], v[8:9], v[4:5]
	v_lshl_add_u64 v[6:7], v[6:7], 4, s[8:9]
	v_pk_add_f32 v[4:5], v[4:5], v[4:5] op_sel:[0,1] op_sel_hi:[1,0]
	v_lshl_add_u64 v[6:7], s[52:53], 2, v[6:7]
	global_store_dword v[6:7], v4, off sc1

.LBB0_522:
	s_lshl_b32 s0, s38, 8
	v_mov_b32_e32 v243, v239
	v_mov_b32_e32 v250, v238
	s_or_b32 s0, s0, s55
	s_lshl_b32 s86, s83, 8
	v_lshl_add_u32 v216, v250, 3, s0
	s_ashr_i32 s0, s83, 5
	s_mul_hi_i32 s1, s0, 0x2400
	s_mulk_i32 s0, 0x2400
	s_lshl_b64 s[52:53], s[0:1], 2
	s_add_u32 s0, s20, s52
	s_addc_u32 s1, s21, s53
	v_ashrrev_i32_e32 v217, 31, v216
	v_lshl_add_u64 v[126:127], v[216:217], 2, s[0:1]
	global_load_dwordx2 v[228:229], v[126:127], off offset:16
	global_load_dwordx2 v[226:227], v[126:127], off offset:24
	global_load_dwordx2 v[236:237], v[126:127], off
	global_load_dwordx2 v[234:235], v[126:127], off offset:8
	global_load_dwordx2 v[220:221], v[126:127], off offset:528
	global_load_dwordx2 v[218:219], v[126:127], off offset:536
	global_load_dwordx2 v[232:233], v[126:127], off offset:512
	global_load_dwordx2 v[230:231], v[126:127], off offset:520
	s_mov_b32 s25, s24
	v_add_u32_e32 v249, s43, v243
	v_cmp_eq_u32_e32 vcc, 0, v250
	v_add_u32_e32 v114, s86, v249
	v_readlane_b32 s0, v255, 19
	v_readlane_b32 s1, v255, 20
	v_ashrrev_i32_e32 v115, 31, v114
	v_lshl_add_u64 v[116:117], v[216:217], 1, s[0:1]
	v_lshlrev_b64 v[214:215], 11, v[114:115]
	v_lshl_add_u64 v[114:115], v[116:117], 0, v[214:215]
	global_load_dwordx4 v[222:225], v[114:115], off
	global_load_dwordx4 v[186:189], v[114:115], off offset:256
	s_mov_b64 s[0:1], 0x8000
	v_lshl_add_u64 v[212:213], v[214:215], 0, s[0:1]
	s_mov_b64 s[0:1], 0x10000
	v_lshl_add_u64 v[114:115], v[116:117], 0, v[212:213]
	v_lshl_add_u64 v[210:211], v[214:215], 0, s[0:1]
	s_mov_b64 s[0:1], 0x18000
	global_load_dwordx4 v[182:185], v[114:115], off
	global_load_dwordx4 v[178:181], v[114:115], off offset:256
	v_lshl_add_u64 v[114:115], v[116:117], 0, v[210:211]
	v_lshl_add_u64 v[208:209], v[214:215], 0, s[0:1]
	global_load_dwordx4 v[174:177], v[114:115], off
	global_load_dwordx4 v[170:173], v[114:115], off offset:256
	v_lshl_add_u64 v[114:115], v[116:117], 0, v[208:209]
	v_lshl_add_u64 v[206:207], v[214:215], 0, s[58:59]
	s_mov_b64 s[0:1], 0x48000
	global_load_dwordx4 v[166:169], v[114:115], off
	global_load_dwordx4 v[162:165], v[114:115], off offset:256
	v_lshl_add_u64 v[114:115], v[116:117], 0, v[206:207]
	v_lshl_add_u64 v[204:205], v[214:215], 0, s[0:1]
	s_mov_b64 s[0:1], 0x50000
	global_load_dwordx4 v[158:161], v[114:115], off
	global_load_dwordx4 v[154:157], v[114:115], off offset:256
	v_lshl_add_u64 v[114:115], v[116:117], 0, v[204:205]
	v_lshl_add_u64 v[202:203], v[214:215], 0, s[0:1]
	s_mov_b64 s[0:1], 0x58000
	global_load_dwordx4 v[150:153], v[114:115], off
	global_load_dwordx4 v[146:149], v[114:115], off offset:256
	v_lshl_add_u64 v[114:115], v[116:117], 0, v[202:203]
	v_lshl_add_u64 v[200:201], v[214:215], 0, s[0:1]
	global_load_dwordx4 v[134:137], v[114:115], off
	global_load_dwordx4 v[126:129], v[114:115], off offset:256
	v_lshl_add_u64 v[114:115], v[116:117], 0, v[200:201]
	global_load_dwordx4 v[122:125], v[114:115], off
	s_nop 0
	global_load_dwordx4 v[114:117], v[114:115], off offset:256
	v_readlane_b32 s0, v255, 42
	v_readlane_b32 s1, v255, 43
	s_waitcnt vmcnt(16)
	v_pk_mul_f32 v[226:227], s[24:25], v[226:227]
	v_pk_mul_f32 v[234:235], v[234:235], s[24:25]
	v_pk_mul_f32 v[236:237], v[236:237], s[0:1]
	v_pk_mul_f32 v[228:229], s[0:1], v[228:229]
	v_pk_mul_f32 v[220:221], s[0:1], v[220:221]
	v_pk_mul_f32 v[232:233], s[0:1], v[232:233]
	v_pk_mul_f32 v[218:219], s[24:25], v[218:219]
	v_pk_mul_f32 v[230:231], s[24:25], v[230:231]
	s_waitcnt vmcnt(15)
	v_cvt_f32_f16_e32 v252, v222
	v_cvt_f32_f16_sdwa v253, v222 dst_sel:DWORD dst_unused:UNUSED_PAD src0_sel:WORD_1
	v_cvt_f32_f16_e32 v222, v223
	v_cvt_f32_f16_sdwa v223, v223 dst_sel:DWORD dst_unused:UNUSED_PAD src0_sel:WORD_1
	v_pk_fma_f32 v[142:143], v[142:143], v[236:237], v[252:253]
	v_pk_fma_f32 v[144:145], v[144:145], v[234:235], v[222:223]
	v_cvt_f32_f16_e32 v222, v224
	v_cvt_f32_f16_sdwa v223, v224 dst_sel:DWORD dst_unused:UNUSED_PAD src0_sel:WORD_1
	v_cvt_f32_f16_e32 v224, v225
	v_cvt_f32_f16_sdwa v225, v225 dst_sel:DWORD dst_unused:UNUSED_PAD src0_sel:WORD_1
	v_pk_fma_f32 v[138:139], v[138:139], v[228:229], v[222:223]
	s_waitcnt vmcnt(14)
	v_cvt_f32_f16_e32 v222, v186
	v_cvt_f32_f16_sdwa v223, v186 dst_sel:DWORD dst_unused:UNUSED_PAD src0_sel:WORD_1
	v_cvt_f32_f16_e32 v186, v187
	v_cvt_f32_f16_sdwa v187, v187 dst_sel:DWORD dst_unused:UNUSED_PAD src0_sel:WORD_1
	v_pk_fma_f32 v[140:141], v[140:141], v[226:227], v[224:225]
	v_pk_fma_f32 v[130:131], v[130:131], v[232:233], v[222:223]
	v_pk_fma_f32 v[132:133], v[132:133], v[230:231], v[186:187]
	v_cvt_f32_f16_e32 v186, v188
	v_cvt_f32_f16_sdwa v187, v188 dst_sel:DWORD dst_unused:UNUSED_PAD src0_sel:WORD_1
	v_cvt_f32_f16_e32 v188, v189
	v_cvt_f32_f16_sdwa v189, v189 dst_sel:DWORD dst_unused:UNUSED_PAD src0_sel:WORD_1
	v_pk_fma_f32 v[118:119], v[118:119], v[220:221], v[186:187]
	v_mul_f32_e32 v186, v143, v143
	v_mul_f32_e32 v187, v145, v145
	v_fmac_f32_e32 v186, v142, v142
	v_fmac_f32_e32 v187, v144, v144
	v_pk_fma_f32 v[120:121], v[120:121], v[218:219], v[188:189]
	v_add_f32_e32 v186, v186, v187
	v_mul_f32_e32 v187, v139, v139
	v_mul_f32_e32 v188, v141, v141
	v_fmac_f32_e32 v187, v138, v138
	v_fmac_f32_e32 v188, v140, v140
	v_add_f32_e32 v187, v187, v188
	v_add_f32_e32 v186, v186, v187
	v_mul_f32_e32 v187, v131, v131
	v_mul_f32_e32 v188, v133, v133
	v_fmac_f32_e32 v187, v130, v130
	v_fmac_f32_e32 v188, v132, v132
	v_add_f32_e32 v187, v187, v188
	v_add_f32_e32 v186, v186, v187
	v_mul_f32_e32 v187, v119, v119
	v_mul_f32_e32 v188, v121, v121
	v_fmac_f32_e32 v187, v118, v118
	v_fmac_f32_e32 v188, v120, v120
	v_add_f32_e32 v187, v187, v188
	v_add_f32_e32 v186, v187, v186
	ds_swizzle_b32 v187, v186 offset:swizzle(SWAP,16)
	s_waitcnt lgkmcnt(0)
	v_add_f32_e32 v187, v186, v187
	v_mov_b32_e32 v188, v187
	s_nop 1
	v_permlane32_swap_b32_e32 v187, v188
	v_lshl_add_u32 v186, v243, 4, s78
	s_and_saveexec_b64 s[0:1], vcc
	v_add_f32_e32 v187, v187, v188
	ds_write_b32 v186, v187
	s_or_b64 exec, exec, s[0:1]
	s_waitcnt vmcnt(13)
	v_cvt_f32_f16_sdwa v189, v182 dst_sel:DWORD dst_unused:UNUSED_PAD src0_sel:WORD_1
	v_cvt_f32_f16_e32 v188, v182
	v_cvt_f32_f16_sdwa v223, v183 dst_sel:DWORD dst_unused:UNUSED_PAD src0_sel:WORD_1
	v_cvt_f32_f16_e32 v222, v183
	v_cvt_f32_f16_sdwa v183, v184 dst_sel:DWORD dst_unused:UNUSED_PAD src0_sel:WORD_1
	v_cvt_f32_f16_e32 v182, v184
	v_pk_fma_f32 v[110:111], v[110:111], v[236:237], v[188:189]
	v_cvt_f32_f16_sdwa v189, v185 dst_sel:DWORD dst_unused:UNUSED_PAD src0_sel:WORD_1
	v_cvt_f32_f16_e32 v188, v185
	v_pk_fma_f32 v[106:107], v[106:107], v[228:229], v[182:183]
	s_waitcnt vmcnt(12)
	v_cvt_f32_f16_sdwa v183, v178 dst_sel:DWORD dst_unused:UNUSED_PAD src0_sel:WORD_1
	v_cvt_f32_f16_e32 v182, v178
	v_cvt_f32_f16_sdwa v185, v179 dst_sel:DWORD dst_unused:UNUSED_PAD src0_sel:WORD_1
	v_cvt_f32_f16_e32 v184, v179
	v_cvt_f32_f16_sdwa v179, v180 dst_sel:DWORD dst_unused:UNUSED_PAD src0_sel:WORD_1
	v_cvt_f32_f16_e32 v178, v180
	v_pk_fma_f32 v[112:113], v[112:113], v[234:235], v[222:223]
	v_pk_fma_f32 v[108:109], v[108:109], v[226:227], v[188:189]
	v_pk_fma_f32 v[102:103], v[102:103], v[232:233], v[182:183]
	v_pk_fma_f32 v[98:99], v[98:99], v[220:221], v[178:179]
	v_mul_f32_e32 v178, v111, v111
	v_mul_f32_e32 v179, v113, v113
	v_fmac_f32_e32 v178, v110, v110
	v_fmac_f32_e32 v179, v112, v112
	v_add_f32_e32 v178, v178, v179
	v_mul_f32_e32 v179, v107, v107
	v_mul_f32_e32 v180, v109, v109
	v_cvt_f32_f16_sdwa v183, v181 dst_sel:DWORD dst_unused:UNUSED_PAD src0_sel:WORD_1
	v_cvt_f32_f16_e32 v182, v181
	v_fmac_f32_e32 v179, v106, v106
	v_fmac_f32_e32 v180, v108, v108
	v_pk_fma_f32 v[104:105], v[104:105], v[230:231], v[184:185]
	v_add_f32_e32 v179, v179, v180
	v_add_f32_e32 v178, v178, v179
	v_mul_f32_e32 v179, v103, v103
	v_mul_f32_e32 v180, v105, v105
	v_fmac_f32_e32 v179, v102, v102
	v_fmac_f32_e32 v180, v104, v104
	v_pk_fma_f32 v[100:101], v[100:101], v[218:219], v[182:183]
	v_add_f32_e32 v179, v179, v180
	v_add_f32_e32 v178, v178, v179
	v_mul_f32_e32 v179, v99, v99
	v_mul_f32_e32 v180, v101, v101
	v_fmac_f32_e32 v179, v98, v98
	v_fmac_f32_e32 v180, v100, v100
	v_add_f32_e32 v179, v179, v180
	v_add_f32_e32 v178, v179, v178
	ds_swizzle_b32 v179, v178 offset:swizzle(SWAP,16)
	s_waitcnt lgkmcnt(0)
	v_add_f32_e32 v178, v178, v179
	v_mov_b32_e32 v179, v178
	s_nop 1
	v_permlane32_swap_b32_e32 v178, v179
	s_and_saveexec_b64 s[0:1], vcc
	v_add_f32_e32 v178, v178, v179
	ds_write_b32 v186, v178 offset:256
	s_or_b64 exec, exec, s[0:1]
	s_waitcnt vmcnt(11)
	v_cvt_f32_f16_sdwa v179, v174 dst_sel:DWORD dst_unused:UNUSED_PAD src0_sel:WORD_1
	v_cvt_f32_f16_e32 v178, v174
	v_cvt_f32_f16_sdwa v181, v175 dst_sel:DWORD dst_unused:UNUSED_PAD src0_sel:WORD_1
	v_cvt_f32_f16_e32 v180, v175
	v_cvt_f32_f16_sdwa v175, v176 dst_sel:DWORD dst_unused:UNUSED_PAD src0_sel:WORD_1
	v_cvt_f32_f16_e32 v174, v176
	v_pk_fma_f32 v[94:95], v[94:95], v[236:237], v[178:179]
	v_cvt_f32_f16_sdwa v179, v177 dst_sel:DWORD dst_unused:UNUSED_PAD src0_sel:WORD_1
	v_cvt_f32_f16_e32 v178, v177
	v_pk_fma_f32 v[90:91], v[90:91], v[228:229], v[174:175]
	s_waitcnt vmcnt(10)
	v_cvt_f32_f16_sdwa v175, v170 dst_sel:DWORD dst_unused:UNUSED_PAD src0_sel:WORD_1
	v_cvt_f32_f16_e32 v174, v170
	v_cvt_f32_f16_sdwa v177, v171 dst_sel:DWORD dst_unused:UNUSED_PAD src0_sel:WORD_1
	v_cvt_f32_f16_e32 v176, v171
	v_cvt_f32_f16_sdwa v171, v172 dst_sel:DWORD dst_unused:UNUSED_PAD src0_sel:WORD_1
	v_cvt_f32_f16_e32 v170, v172
	v_pk_fma_f32 v[96:97], v[96:97], v[234:235], v[180:181]
	v_pk_fma_f32 v[92:93], v[92:93], v[226:227], v[178:179]
	v_pk_fma_f32 v[86:87], v[86:87], v[232:233], v[174:175]
	v_pk_fma_f32 v[82:83], v[82:83], v[220:221], v[170:171]
	v_mul_f32_e32 v170, v95, v95
	v_mul_f32_e32 v171, v97, v97
	v_fmac_f32_e32 v170, v94, v94
	v_fmac_f32_e32 v171, v96, v96
	v_add_f32_e32 v170, v170, v171
	v_mul_f32_e32 v171, v91, v91
	v_mul_f32_e32 v172, v93, v93
	v_cvt_f32_f16_sdwa v175, v173 dst_sel:DWORD dst_unused:UNUSED_PAD src0_sel:WORD_1
	v_cvt_f32_f16_e32 v174, v173
	v_fmac_f32_e32 v171, v90, v90
	v_fmac_f32_e32 v172, v92, v92
	v_pk_fma_f32 v[88:89], v[88:89], v[230:231], v[176:177]
	v_add_f32_e32 v171, v171, v172
	v_add_f32_e32 v170, v170, v171
	v_mul_f32_e32 v171, v87, v87
	v_mul_f32_e32 v172, v89, v89
	v_fmac_f32_e32 v171, v86, v86
	v_fmac_f32_e32 v172, v88, v88
	v_pk_fma_f32 v[84:85], v[84:85], v[218:219], v[174:175]
	v_add_f32_e32 v171, v171, v172
	v_add_f32_e32 v170, v170, v171
	v_mul_f32_e32 v171, v83, v83
	v_mul_f32_e32 v172, v85, v85
	v_fmac_f32_e32 v171, v82, v82
	v_fmac_f32_e32 v172, v84, v84
	v_add_f32_e32 v171, v171, v172
	v_add_f32_e32 v170, v171, v170
	ds_swizzle_b32 v171, v170 offset:swizzle(SWAP,16)
	s_waitcnt lgkmcnt(0)
	v_add_f32_e32 v170, v170, v171
	v_mov_b32_e32 v171, v170
	s_nop 1
	v_permlane32_swap_b32_e32 v170, v171
	s_mov_b64 s[0:1], exec
	s_and_b64 s[2:3], s[0:1], vcc
	v_mov_b32_e32 v252, v242
	s_mov_b64 exec, s[2:3]
	v_add_f32_e32 v170, v170, v171
	ds_write_b32 v186, v170 offset:512
	s_or_b64 exec, exec, s[0:1]
	s_waitcnt vmcnt(9)
	v_cvt_f32_f16_sdwa v171, v166 dst_sel:DWORD dst_unused:UNUSED_PAD src0_sel:WORD_1
	v_cvt_f32_f16_e32 v170, v166
	v_cvt_f32_f16_sdwa v173, v167 dst_sel:DWORD dst_unused:UNUSED_PAD src0_sel:WORD_1
	v_cvt_f32_f16_e32 v172, v167
	v_cvt_f32_f16_sdwa v167, v168 dst_sel:DWORD dst_unused:UNUSED_PAD src0_sel:WORD_1
	v_cvt_f32_f16_e32 v166, v168
	v_pk_fma_f32 v[78:79], v[78:79], v[236:237], v[170:171]
	v_cvt_f32_f16_sdwa v171, v169 dst_sel:DWORD dst_unused:UNUSED_PAD src0_sel:WORD_1
	v_cvt_f32_f16_e32 v170, v169
	v_pk_fma_f32 v[74:75], v[74:75], v[228:229], v[166:167]
	s_waitcnt vmcnt(8)
	v_cvt_f32_f16_sdwa v167, v162 dst_sel:DWORD dst_unused:UNUSED_PAD src0_sel:WORD_1
	v_cvt_f32_f16_e32 v166, v162
	v_cvt_f32_f16_sdwa v169, v163 dst_sel:DWORD dst_unused:UNUSED_PAD src0_sel:WORD_1
	v_cvt_f32_f16_e32 v168, v163
	v_cvt_f32_f16_sdwa v163, v164 dst_sel:DWORD dst_unused:UNUSED_PAD src0_sel:WORD_1
	v_cvt_f32_f16_e32 v162, v164
	v_pk_fma_f32 v[80:81], v[80:81], v[234:235], v[172:173]
	v_pk_fma_f32 v[76:77], v[76:77], v[226:227], v[170:171]
	v_pk_fma_f32 v[70:71], v[70:71], v[232:233], v[166:167]
	v_pk_fma_f32 v[66:67], v[66:67], v[220:221], v[162:163]
	v_mul_f32_e32 v162, v79, v79
	v_mul_f32_e32 v163, v81, v81
	v_fmac_f32_e32 v162, v78, v78
	v_fmac_f32_e32 v163, v80, v80
	v_add_f32_e32 v162, v162, v163
	v_mul_f32_e32 v163, v75, v75
	v_mul_f32_e32 v164, v77, v77
	v_cvt_f32_f16_sdwa v167, v165 dst_sel:DWORD dst_unused:UNUSED_PAD src0_sel:WORD_1
	v_cvt_f32_f16_e32 v166, v165
	v_fmac_f32_e32 v163, v74, v74
	v_fmac_f32_e32 v164, v76, v76
	v_pk_fma_f32 v[72:73], v[72:73], v[230:231], v[168:169]
	v_add_f32_e32 v163, v163, v164
	v_add_f32_e32 v162, v162, v163
	v_mul_f32_e32 v163, v71, v71
	v_mul_f32_e32 v164, v73, v73
	v_fmac_f32_e32 v163, v70, v70
	v_fmac_f32_e32 v164, v72, v72
	v_pk_fma_f32 v[68:69], v[68:69], v[218:219], v[166:167]
	v_add_f32_e32 v163, v163, v164
	v_add_f32_e32 v162, v162, v163
	v_mul_f32_e32 v163, v67, v67
	v_mul_f32_e32 v164, v69, v69
	v_fmac_f32_e32 v163, v66, v66
	v_fmac_f32_e32 v164, v68, v68
	v_add_f32_e32 v163, v163, v164
	v_add_f32_e32 v162, v163, v162
	ds_swizzle_b32 v163, v162 offset:swizzle(SWAP,16)
	s_waitcnt lgkmcnt(0)
	v_add_f32_e32 v162, v162, v163
	v_mov_b32_e32 v163, v162
	s_nop 1
	v_permlane32_swap_b32_e32 v162, v163
	s_and_saveexec_b64 s[0:1], vcc
	v_add_f32_e32 v162, v162, v163
	ds_write_b32 v186, v162 offset:768
	s_or_b64 exec, exec, s[0:1]
	s_waitcnt vmcnt(7)
	v_cvt_f32_f16_sdwa v163, v158 dst_sel:DWORD dst_unused:UNUSED_PAD src0_sel:WORD_1
	v_cvt_f32_f16_e32 v162, v158
	v_cvt_f32_f16_sdwa v165, v159 dst_sel:DWORD dst_unused:UNUSED_PAD src0_sel:WORD_1
	v_cvt_f32_f16_e32 v164, v159
	v_cvt_f32_f16_sdwa v159, v160 dst_sel:DWORD dst_unused:UNUSED_PAD src0_sel:WORD_1
	v_cvt_f32_f16_e32 v158, v160
	v_pk_fma_f32 v[62:63], v[62:63], v[236:237], v[162:163]
	v_cvt_f32_f16_sdwa v163, v161 dst_sel:DWORD dst_unused:UNUSED_PAD src0_sel:WORD_1
	v_cvt_f32_f16_e32 v162, v161
	v_pk_fma_f32 v[58:59], v[58:59], v[228:229], v[158:159]
	s_waitcnt vmcnt(6)
	v_cvt_f32_f16_sdwa v159, v154 dst_sel:DWORD dst_unused:UNUSED_PAD src0_sel:WORD_1
	v_cvt_f32_f16_e32 v158, v154
	v_cvt_f32_f16_sdwa v161, v155 dst_sel:DWORD dst_unused:UNUSED_PAD src0_sel:WORD_1
	v_cvt_f32_f16_e32 v160, v155
	v_cvt_f32_f16_sdwa v155, v156 dst_sel:DWORD dst_unused:UNUSED_PAD src0_sel:WORD_1
	v_cvt_f32_f16_e32 v154, v156
	v_pk_fma_f32 v[64:65], v[64:65], v[234:235], v[164:165]
	v_pk_fma_f32 v[60:61], v[60:61], v[226:227], v[162:163]
	v_pk_fma_f32 v[54:55], v[54:55], v[232:233], v[158:159]
	v_pk_fma_f32 v[50:51], v[50:51], v[220:221], v[154:155]
	v_mul_f32_e32 v154, v63, v63
	v_mul_f32_e32 v155, v65, v65
	v_fmac_f32_e32 v154, v62, v62
	v_fmac_f32_e32 v155, v64, v64
	v_add_f32_e32 v154, v154, v155
	v_mul_f32_e32 v155, v59, v59
	v_mul_f32_e32 v156, v61, v61
	v_cvt_f32_f16_sdwa v159, v157 dst_sel:DWORD dst_unused:UNUSED_PAD src0_sel:WORD_1
	v_cvt_f32_f16_e32 v158, v157
	v_fmac_f32_e32 v155, v58, v58
	v_fmac_f32_e32 v156, v60, v60
	v_pk_fma_f32 v[56:57], v[56:57], v[230:231], v[160:161]
	v_add_f32_e32 v155, v155, v156
	v_add_f32_e32 v154, v154, v155
	v_mul_f32_e32 v155, v55, v55
	v_mul_f32_e32 v156, v57, v57
	v_fmac_f32_e32 v155, v54, v54
	v_fmac_f32_e32 v156, v56, v56
	v_pk_fma_f32 v[52:53], v[52:53], v[218:219], v[158:159]
	v_add_f32_e32 v155, v155, v156
	v_add_f32_e32 v154, v154, v155
	v_mul_f32_e32 v155, v51, v51
	v_mul_f32_e32 v156, v53, v53
	v_fmac_f32_e32 v155, v50, v50
	v_fmac_f32_e32 v156, v52, v52
	v_add_f32_e32 v155, v155, v156
	v_add_f32_e32 v154, v155, v154
	ds_swizzle_b32 v155, v154 offset:swizzle(SWAP,16)
	s_waitcnt lgkmcnt(0)
	v_add_f32_e32 v154, v154, v155
	v_mov_b32_e32 v155, v154
	s_nop 1
	v_permlane32_swap_b32_e32 v154, v155
	s_and_saveexec_b64 s[0:1], vcc
	v_add_f32_e32 v154, v154, v155
	ds_write_b32 v186, v154 offset:2048
	s_or_b64 exec, exec, s[0:1]
	s_waitcnt vmcnt(5)
	v_cvt_f32_f16_sdwa v155, v150 dst_sel:DWORD dst_unused:UNUSED_PAD src0_sel:WORD_1
	v_cvt_f32_f16_e32 v154, v150
	v_cvt_f32_f16_sdwa v157, v151 dst_sel:DWORD dst_unused:UNUSED_PAD src0_sel:WORD_1
	v_cvt_f32_f16_e32 v156, v151
	v_cvt_f32_f16_sdwa v151, v152 dst_sel:DWORD dst_unused:UNUSED_PAD src0_sel:WORD_1
	v_cvt_f32_f16_e32 v150, v152
	v_pk_fma_f32 v[46:47], v[46:47], v[236:237], v[154:155]
	v_cvt_f32_f16_sdwa v155, v153 dst_sel:DWORD dst_unused:UNUSED_PAD src0_sel:WORD_1
	v_cvt_f32_f16_e32 v154, v153
	v_pk_fma_f32 v[42:43], v[42:43], v[228:229], v[150:151]
	s_waitcnt vmcnt(4)
	v_cvt_f32_f16_sdwa v151, v146 dst_sel:DWORD dst_unused:UNUSED_PAD src0_sel:WORD_1
	v_cvt_f32_f16_e32 v150, v146
	v_cvt_f32_f16_sdwa v153, v147 dst_sel:DWORD dst_unused:UNUSED_PAD src0_sel:WORD_1
	v_cvt_f32_f16_e32 v152, v147
	v_cvt_f32_f16_sdwa v147, v148 dst_sel:DWORD dst_unused:UNUSED_PAD src0_sel:WORD_1
	v_cvt_f32_f16_e32 v146, v148
	v_pk_fma_f32 v[48:49], v[48:49], v[234:235], v[156:157]
	v_pk_fma_f32 v[44:45], v[44:45], v[226:227], v[154:155]
	v_pk_fma_f32 v[38:39], v[38:39], v[232:233], v[150:151]
	v_pk_fma_f32 v[34:35], v[34:35], v[220:221], v[146:147]
	v_mul_f32_e32 v146, v47, v47
	v_mul_f32_e32 v147, v49, v49
	v_fmac_f32_e32 v146, v46, v46
	v_fmac_f32_e32 v147, v48, v48
	v_add_f32_e32 v146, v146, v147
	v_mul_f32_e32 v147, v43, v43
	v_mul_f32_e32 v148, v45, v45
	v_cvt_f32_f16_sdwa v151, v149 dst_sel:DWORD dst_unused:UNUSED_PAD src0_sel:WORD_1
	v_cvt_f32_f16_e32 v150, v149
	v_fmac_f32_e32 v147, v42, v42
	v_fmac_f32_e32 v148, v44, v44
	v_pk_fma_f32 v[40:41], v[40:41], v[230:231], v[152:153]
	v_add_f32_e32 v147, v147, v148
	v_add_f32_e32 v146, v146, v147
	v_mul_f32_e32 v147, v39, v39
	v_mul_f32_e32 v148, v41, v41
	v_fmac_f32_e32 v147, v38, v38
	v_fmac_f32_e32 v148, v40, v40
	v_pk_fma_f32 v[36:37], v[36:37], v[218:219], v[150:151]
	v_add_f32_e32 v147, v147, v148
	v_add_f32_e32 v146, v146, v147
	v_mul_f32_e32 v147, v35, v35
	v_mul_f32_e32 v148, v37, v37
	v_fmac_f32_e32 v147, v34, v34
	v_fmac_f32_e32 v148, v36, v36
	v_add_f32_e32 v147, v147, v148
	v_add_f32_e32 v146, v147, v146
	ds_swizzle_b32 v147, v146 offset:swizzle(SWAP,16)
	s_waitcnt lgkmcnt(0)
	v_add_f32_e32 v146, v146, v147
	v_mov_b32_e32 v147, v146
	s_nop 1
	v_permlane32_swap_b32_e32 v146, v147
	s_and_saveexec_b64 s[0:1], vcc
	v_add_f32_e32 v146, v146, v147
	ds_write_b32 v186, v146 offset:2304
	s_or_b64 exec, exec, s[0:1]
	s_waitcnt vmcnt(3)
	v_cvt_f32_f16_sdwa v147, v134 dst_sel:DWORD dst_unused:UNUSED_PAD src0_sel:WORD_1
	v_cvt_f32_f16_e32 v146, v134
	v_cvt_f32_f16_sdwa v149, v135 dst_sel:DWORD dst_unused:UNUSED_PAD src0_sel:WORD_1
	v_cvt_f32_f16_e32 v148, v135
	v_cvt_f32_f16_sdwa v135, v136 dst_sel:DWORD dst_unused:UNUSED_PAD src0_sel:WORD_1
	v_cvt_f32_f16_e32 v134, v136
	v_pk_fma_f32 v[30:31], v[30:31], v[236:237], v[146:147]
	v_cvt_f32_f16_sdwa v147, v137 dst_sel:DWORD dst_unused:UNUSED_PAD src0_sel:WORD_1
	v_cvt_f32_f16_e32 v146, v137
	v_pk_fma_f32 v[26:27], v[26:27], v[228:229], v[134:135]
	s_waitcnt vmcnt(2)
	v_cvt_f32_f16_sdwa v135, v126 dst_sel:DWORD dst_unused:UNUSED_PAD src0_sel:WORD_1
	v_cvt_f32_f16_e32 v134, v126
	v_cvt_f32_f16_sdwa v137, v127 dst_sel:DWORD dst_unused:UNUSED_PAD src0_sel:WORD_1
	v_cvt_f32_f16_e32 v136, v127
	v_cvt_f32_f16_sdwa v127, v128 dst_sel:DWORD dst_unused:UNUSED_PAD src0_sel:WORD_1
	v_cvt_f32_f16_e32 v126, v128
	v_pk_fma_f32 v[32:33], v[32:33], v[234:235], v[148:149]
	v_pk_fma_f32 v[28:29], v[28:29], v[226:227], v[146:147]
	v_pk_fma_f32 v[22:23], v[22:23], v[232:233], v[134:135]
	v_pk_fma_f32 v[18:19], v[18:19], v[220:221], v[126:127]
	v_mul_f32_e32 v126, v31, v31
	v_mul_f32_e32 v127, v33, v33
	v_fmac_f32_e32 v126, v30, v30
	v_fmac_f32_e32 v127, v32, v32
	v_add_f32_e32 v126, v126, v127
	v_mul_f32_e32 v127, v27, v27
	v_mul_f32_e32 v128, v29, v29
	v_cvt_f32_f16_sdwa v135, v129 dst_sel:DWORD dst_unused:UNUSED_PAD src0_sel:WORD_1
	v_cvt_f32_f16_e32 v134, v129
	v_fmac_f32_e32 v127, v26, v26
	v_fmac_f32_e32 v128, v28, v28
	v_pk_fma_f32 v[24:25], v[24:25], v[230:231], v[136:137]
	v_add_f32_e32 v127, v127, v128
	v_add_f32_e32 v126, v126, v127
	v_mul_f32_e32 v127, v23, v23
	v_mul_f32_e32 v128, v25, v25
	v_fmac_f32_e32 v127, v22, v22
	v_fmac_f32_e32 v128, v24, v24
	v_pk_fma_f32 v[20:21], v[20:21], v[218:219], v[134:135]
	v_add_f32_e32 v127, v127, v128
	v_add_f32_e32 v126, v126, v127
	v_mul_f32_e32 v127, v19, v19
	v_mul_f32_e32 v128, v21, v21
	v_fmac_f32_e32 v127, v18, v18
	v_fmac_f32_e32 v128, v20, v20
	v_add_f32_e32 v127, v127, v128
	v_add_f32_e32 v126, v127, v126
	ds_swizzle_b32 v127, v126 offset:swizzle(SWAP,16)
	s_waitcnt lgkmcnt(0)
	v_add_f32_e32 v126, v126, v127
	v_mov_b32_e32 v127, v126
	s_nop 1
	v_permlane32_swap_b32_e32 v126, v127
	s_and_saveexec_b64 s[0:1], vcc
	v_add_f32_e32 v126, v126, v127
	ds_write_b32 v186, v126 offset:2560
	s_or_b64 exec, exec, s[0:1]
	s_waitcnt vmcnt(1)
	v_cvt_f32_f16_sdwa v127, v122 dst_sel:DWORD dst_unused:UNUSED_PAD src0_sel:WORD_1
	v_cvt_f32_f16_e32 v126, v122
	v_cvt_f32_f16_sdwa v129, v123 dst_sel:DWORD dst_unused:UNUSED_PAD src0_sel:WORD_1
	v_cvt_f32_f16_e32 v128, v123
	v_pk_fma_f32 v[126:127], v[14:15], v[236:237], v[126:127]
	v_cvt_f32_f16_sdwa v15, v124 dst_sel:DWORD dst_unused:UNUSED_PAD src0_sel:WORD_1
	v_cvt_f32_f16_e32 v14, v124
	v_pk_fma_f32 v[122:123], v[16:17], v[234:235], v[128:129]
	v_cvt_f32_f16_sdwa v17, v125 dst_sel:DWORD dst_unused:UNUSED_PAD src0_sel:WORD_1
	v_cvt_f32_f16_e32 v16, v125
	v_pk_fma_f32 v[134:135], v[10:11], v[228:229], v[14:15]
	s_waitcnt vmcnt(0)
	v_cvt_f32_f16_sdwa v11, v114 dst_sel:DWORD dst_unused:UNUSED_PAD src0_sel:WORD_1
	v_cvt_f32_f16_e32 v10, v114
	v_pk_fma_f32 v[128:129], v[12:13], v[226:227], v[16:17]
	v_cvt_f32_f16_sdwa v13, v115 dst_sel:DWORD dst_unused:UNUSED_PAD src0_sel:WORD_1
	v_cvt_f32_f16_e32 v12, v115
	v_pk_fma_f32 v[124:125], v[6:7], v[232:233], v[10:11]
	v_cvt_f32_f16_sdwa v7, v116 dst_sel:DWORD dst_unused:UNUSED_PAD src0_sel:WORD_1
	v_cvt_f32_f16_e32 v6, v116
	v_pk_fma_f32 v[114:115], v[8:9], v[230:231], v[12:13]
	v_cvt_f32_f16_sdwa v9, v117 dst_sel:DWORD dst_unused:UNUSED_PAD src0_sel:WORD_1
	v_cvt_f32_f16_e32 v8, v117
	v_pk_fma_f32 v[136:137], v[2:3], v[220:221], v[6:7]
	v_mul_f32_e32 v2, v127, v127
	v_mul_f32_e32 v3, v123, v123
	v_fmac_f32_e32 v2, v126, v126
	v_fmac_f32_e32 v3, v122, v122
	v_pk_fma_f32 v[116:117], v[4:5], v[218:219], v[8:9]
	v_add_f32_e32 v2, v2, v3
	v_mul_f32_e32 v3, v135, v135
	v_mul_f32_e32 v4, v129, v129
	v_fmac_f32_e32 v3, v134, v134
	v_fmac_f32_e32 v4, v128, v128
	v_add_f32_e32 v3, v3, v4
	v_add_f32_e32 v2, v2, v3
	v_mul_f32_e32 v3, v125, v125
	v_mul_f32_e32 v4, v115, v115
	v_fmac_f32_e32 v3, v124, v124
	v_fmac_f32_e32 v4, v114, v114
	v_add_f32_e32 v3, v3, v4
	v_add_f32_e32 v2, v2, v3
	v_mul_f32_e32 v3, v137, v137
	v_mul_f32_e32 v4, v117, v117
	v_fmac_f32_e32 v3, v136, v136
	v_fmac_f32_e32 v4, v116, v116
	v_add_f32_e32 v3, v3, v4
	v_add_f32_e32 v2, v3, v2
	ds_swizzle_b32 v3, v2 offset:swizzle(SWAP,16)
	s_waitcnt lgkmcnt(0)
	v_add_f32_e32 v2, v2, v3
	v_mov_b32_e32 v3, v2
	s_nop 1
	v_permlane32_swap_b32_e32 v2, v3
	s_and_saveexec_b64 s[0:1], vcc
	v_add_f32_e32 v2, v2, v3
	ds_write_b32 v186, v2 offset:2816
	s_or_b64 exec, exec, s[0:1]
	s_waitcnt lgkmcnt(0)
	s_barrier
	v_lshl_add_u32 v3, v250, 4, v243
	v_cmp_gt_i32_e64 s[6:7], 32, v3
	v_and_or_b32 v2, v3, 31, s69
	s_and_saveexec_b64 s[0:1], s[6:7]
	s_cbranch_execz .LBB0_540
	v_lshl_add_u32 v4, v2, 4, 0
	v_add_u32_e32 v4, 0x20400, v4
	ds_read_b128 v[4:7], v4
	s_ashr_i32 s39, s38, 31
	s_waitcnt lgkmcnt(0)
	v_mov_b32_e32 v9, v6
	v_add_u32_e32 v6, s86, v2
	v_mov_b32_e32 v8, v5
	v_mov_b32_e32 v5, v7
	v_ashrrev_i32_e32 v7, 31, v6
	v_pk_add_f32 v[4:5], v[8:9], v[4:5]
	v_lshl_add_u64 v[6:7], v[6:7], 4, s[8:9]
	v_pk_add_f32 v[4:5], v[4:5], v[4:5] op_sel:[0,1] op_sel_hi:[1,0]
	v_lshl_add_u64 v[6:7], s[38:39], 2, v[6:7]
	global_store_dword v[6:7], v4, off sc1

.LBB0_595:
	s_lshl_b32 s0, s52, 8
	v_mov_b32_e32 v193, v189
	v_mov_b32_e32 v194, v188
	s_or_b32 s0, s0, s55
	s_lshl_b32 s2, s14, 8
	v_lshl_add_u32 v166, v194, 3, s0
	s_ashr_i32 s0, s14, 5
	s_mul_hi_i32 s1, s0, 0x2400
	s_mulk_i32 s0, 0x2400
	s_lshl_b64 s[64:65], s[0:1], 2
	s_add_u32 s0, s20, s64
	v_ashrrev_i32_e32 v167, 31, v166
	s_addc_u32 s1, s21, s65
	v_lshlrev_b64 v[156:157], 2, v[166:167]
	v_lshl_add_u64 v[138:139], s[0:1], 0, v[156:157]
	global_load_dwordx2 v[170:171], v[138:139], off offset:16
	global_load_dwordx2 v[168:169], v[138:139], off offset:24
	global_load_dwordx2 v[178:179], v[138:139], off
	global_load_dwordx2 v[176:177], v[138:139], off offset:8
	global_load_dwordx2 v[174:175], v[138:139], off offset:528
	global_load_dwordx2 v[172:173], v[138:139], off offset:536
	global_load_dwordx2 v[182:183], v[138:139], off offset:512
	global_load_dwordx2 v[180:181], v[138:139], off offset:520
	s_mov_b32 s25, s24
	v_add_u32_e32 v192, s43, v193
	v_add_u32_e32 v186, s2, v192
	v_ashrrev_i32_e32 v187, 31, v186
	v_add_u32_e32 v208, 16, v186
	v_ashrrev_i32_e32 v209, 31, v208
	v_lshlrev_b64 v[158:159], 11, v[186:187]
	v_cmp_eq_u32_e32 vcc, 0, v194
	v_readlane_b32 s0, v255, 19
	v_readlane_b32 s1, v255, 20
	v_lshlrev_b64 v[130:131], 12, v[186:187]
	v_lshl_add_u64 v[184:185], s[0:1], 0, v[156:157]
	v_lshl_add_u64 v[130:131], v[184:185], 0, v[130:131]
	global_load_dwordx4 v[162:165], v[130:131], off offset:16
	global_load_dwordx4 v[196:199], v[130:131], off
	global_load_dwordx4 v[200:203], v[130:131], off offset:528
	global_load_dwordx4 v[204:207], v[130:131], off offset:512
	v_lshlrev_b64 v[130:131], 12, v[208:209]
	v_lshl_add_u64 v[134:135], v[184:185], 0, v[130:131]
	global_load_dwordx4 v[138:141], v[134:135], off offset:16
	global_load_dwordx4 v[142:145], v[134:135], off
	global_load_dwordx4 v[130:133], v[134:135], off offset:528
	s_nop 0
	global_load_dwordx4 v[134:137], v[134:135], off offset:512
	v_readlane_b32 s0, v255, 42
	v_readlane_b32 s1, v255, 43
	s_waitcnt vmcnt(8)
	v_pk_mul_f32 v[168:169], s[24:25], v[168:169]
	v_pk_mul_f32 v[176:177], v[176:177], s[24:25]
	v_pk_mul_f32 v[178:179], v[178:179], s[0:1]
	v_pk_mul_f32 v[170:171], s[0:1], v[170:171]
	v_pk_mul_f32 v[174:175], s[0:1], v[174:175]
	v_pk_mul_f32 v[182:183], s[0:1], v[182:183]
	v_pk_mul_f32 v[180:181], s[24:25], v[180:181]
	v_pk_mul_f32 v[172:173], s[24:25], v[172:173]
	s_waitcnt vmcnt(7)
	v_pk_fma_f32 v[124:125], v[124:125], v[168:169], v[164:165]
	s_waitcnt vmcnt(6)
	v_pk_fma_f32 v[160:161], v[126:127], v[178:179], v[196:197]
	v_pk_fma_f32 v[128:129], v[128:129], v[176:177], v[198:199]
	v_pk_fma_f32 v[126:127], v[122:123], v[170:171], v[162:163]
	v_med3_f32 v122, v160, s95, v247
	v_med3_f32 v123, v161, s95, v247
	v_cvt_pk_f16_f32 v162, v122, v123
	v_med3_f32 v122, v128, s95, v247
	v_med3_f32 v123, v129, s95, v247
	v_cvt_pk_f16_f32 v163, v122, v123
	v_med3_f32 v122, v126, s95, v247
	v_med3_f32 v123, v127, s95, v247
	v_cvt_pk_f16_f32 v164, v122, v123
	v_med3_f32 v122, v124, s95, v247
	v_med3_f32 v123, v125, s95, v247
	v_cvt_pk_f16_f32 v165, v122, v123
	v_lshl_add_u64 v[196:197], s[26:27], 0, v[158:159]
	v_lshlrev_b64 v[122:123], 1, v[166:167]
	v_lshl_add_u64 v[166:167], v[196:197], 0, v[122:123]
	s_waitcnt vmcnt(4)
	v_pk_fma_f32 v[118:119], v[118:119], v[182:183], v[204:205]
	global_store_dwordx4 v[166:167], v[162:165], off
	v_pk_fma_f32 v[120:121], v[120:121], v[180:181], v[206:207]
	v_pk_fma_f32 v[114:115], v[114:115], v[174:175], v[200:201]
	v_med3_f32 v162, v118, s95, v247
	v_med3_f32 v163, v119, s95, v247
	v_cvt_pk_f16_f32 v162, v162, v163
	v_med3_f32 v163, v120, s95, v247
	v_med3_f32 v164, v121, s95, v247
	s_waitcnt vmcnt(3)
	v_pk_fma_f32 v[142:143], v[110:111], v[178:179], v[142:143]
	v_pk_fma_f32 v[116:117], v[116:117], v[172:173], v[202:203]
	v_cvt_pk_f16_f32 v163, v163, v164
	v_med3_f32 v164, v114, s95, v247
	v_med3_f32 v165, v115, s95, v247
	v_pk_fma_f32 v[144:145], v[112:113], v[176:177], v[144:145]
	v_pk_fma_f32 v[138:139], v[106:107], v[170:171], v[138:139]
	v_med3_f32 v106, v142, s95, v247
	v_med3_f32 v107, v143, s95, v247
	s_waitcnt vmcnt(1)
	v_pk_fma_f32 v[134:135], v[102:103], v[182:183], v[134:135]
	v_cvt_pk_f16_f32 v164, v164, v165
	v_med3_f32 v165, v116, s95, v247
	v_med3_f32 v187, v117, s95, v247
	v_pk_fma_f32 v[140:141], v[108:109], v[168:169], v[140:141]
	v_cvt_pk_f16_f32 v106, v106, v107
	v_med3_f32 v107, v144, s95, v247
	v_med3_f32 v108, v145, s95, v247
	v_pk_fma_f32 v[136:137], v[104:105], v[180:181], v[136:137]
	v_pk_fma_f32 v[130:131], v[98:99], v[174:175], v[130:131]
	v_med3_f32 v98, v134, s95, v247
	v_med3_f32 v99, v135, s95, v247
	v_cvt_pk_f16_f32 v165, v165, v187
	v_cvt_pk_f16_f32 v107, v107, v108
	v_med3_f32 v108, v138, s95, v247
	v_med3_f32 v109, v139, s95, v247
	v_pk_fma_f32 v[132:133], v[100:101], v[172:173], v[132:133]
	v_cvt_pk_f16_f32 v98, v98, v99
	v_med3_f32 v99, v136, s95, v247
	v_med3_f32 v100, v137, s95, v247
	global_store_dwordx4 v[166:167], v[162:165], off offset:256
	v_cvt_pk_f16_f32 v108, v108, v109
	v_med3_f32 v109, v140, s95, v247
	v_lshlrev_b64 v[162:163], 11, v[208:209]
	v_med3_f32 v110, v141, s95, v247
	v_cvt_pk_f16_f32 v99, v99, v100
	v_med3_f32 v100, v130, s95, v247
	v_med3_f32 v101, v131, s95, v247
	v_cvt_pk_f16_f32 v109, v109, v110
	v_lshl_add_u64 v[110:111], s[26:27], 0, v[162:163]
	v_cvt_pk_f16_f32 v100, v100, v101
	v_med3_f32 v101, v132, s95, v247
	v_med3_f32 v102, v133, s95, v247
	v_add_u32_e32 v164, 32, v186
	v_lshl_add_u64 v[110:111], v[110:111], 0, v[122:123]
	v_cvt_pk_f16_f32 v101, v101, v102
	v_ashrrev_i32_e32 v165, 31, v164
	global_store_dwordx4 v[110:111], v[106:109], off
	global_store_dwordx4 v[110:111], v[98:101], off offset:256
	v_add_u32_e32 v166, 48, v186
	v_ashrrev_i32_e32 v167, 31, v166
	v_lshlrev_b64 v[98:99], 12, v[164:165]
	v_lshl_add_u64 v[98:99], v[184:185], 0, v[98:99]
	global_load_dwordx4 v[196:199], v[98:99], off offset:16
	global_load_dwordx4 v[200:203], v[98:99], off
	global_load_dwordx4 v[204:207], v[98:99], off offset:528
	global_load_dwordx4 v[208:211], v[98:99], off offset:512
	v_lshlrev_b64 v[98:99], 12, v[166:167]
	v_lshl_add_u64 v[102:103], v[184:185], 0, v[98:99]
	global_load_dwordx4 v[106:109], v[102:103], off offset:16
	global_load_dwordx4 v[110:113], v[102:103], off
	global_load_dwordx4 v[98:101], v[102:103], off offset:528
	s_nop 0
	global_load_dwordx4 v[102:105], v[102:103], off offset:512
	v_lshlrev_b64 v[166:167], 11, v[166:167]
	v_lshlrev_b64 v[164:165], 11, v[164:165]
	s_waitcnt vmcnt(7)
	v_pk_fma_f32 v[90:91], v[90:91], v[170:171], v[196:197]
	s_waitcnt vmcnt(6)
	v_pk_fma_f32 v[94:95], v[94:95], v[178:179], v[200:201]
	v_pk_fma_f32 v[96:97], v[96:97], v[176:177], v[202:203]
	s_waitcnt vmcnt(3)
	v_pk_fma_f32 v[106:107], v[74:75], v[170:171], v[106:107]
	s_waitcnt vmcnt(2)
	v_pk_fma_f32 v[110:111], v[78:79], v[178:179], v[110:111]
	v_pk_fma_f32 v[80:81], v[80:81], v[176:177], v[112:113]
	v_med3_f32 v74, v110, s95, v247
	v_med3_f32 v75, v111, s95, v247
	v_pk_fma_f32 v[78:79], v[76:77], v[168:169], v[108:109]
	v_cvt_pk_f16_f32 v74, v74, v75
	v_med3_f32 v75, v80, s95, v247
	v_med3_f32 v76, v81, s95, v247
	v_med3_f32 v187, v94, s95, v247
	v_med3_f32 v195, v95, s95, v247
	v_cvt_pk_f16_f32 v75, v75, v76
	v_med3_f32 v76, v106, s95, v247
	v_med3_f32 v77, v107, s95, v247
	v_cvt_pk_f16_f32 v196, v187, v195
	v_med3_f32 v187, v96, s95, v247
	v_med3_f32 v195, v97, s95, v247
	v_cvt_pk_f16_f32 v76, v76, v77
	v_med3_f32 v77, v78, s95, v247
	v_med3_f32 v108, v79, s95, v247
	v_pk_fma_f32 v[92:93], v[92:93], v[168:169], v[198:199]
	v_cvt_pk_f16_f32 v197, v187, v195
	v_med3_f32 v187, v90, s95, v247
	v_med3_f32 v195, v91, s95, v247
	v_cvt_pk_f16_f32 v77, v77, v108
	v_lshl_add_u64 v[108:109], s[26:27], 0, v[166:167]
	v_cvt_pk_f16_f32 v198, v187, v195
	v_med3_f32 v187, v92, s95, v247
	v_med3_f32 v195, v93, s95, v247
	v_lshl_add_u64 v[200:201], s[26:27], 0, v[164:165]
	v_pk_fma_f32 v[86:87], v[86:87], v[182:183], v[208:209]
	v_lshl_add_u64 v[108:109], v[108:109], 0, v[122:123]
	s_waitcnt vmcnt(0)
	v_pk_fma_f32 v[102:103], v[70:71], v[182:183], v[102:103]
	v_cvt_pk_f16_f32 v199, v187, v195
	v_lshl_add_u64 v[200:201], v[200:201], 0, v[122:123]
	v_pk_fma_f32 v[88:89], v[88:89], v[180:181], v[210:211]
	v_med3_f32 v187, v86, s95, v247
	v_med3_f32 v195, v87, s95, v247
	global_store_dwordx4 v[108:109], v[74:77], off
	v_pk_fma_f32 v[98:99], v[66:67], v[174:175], v[98:99]
	v_med3_f32 v66, v102, s95, v247
	v_pk_fma_f32 v[76:77], v[72:73], v[180:181], v[104:105]
	v_med3_f32 v67, v103, s95, v247
	global_store_dwordx4 v[200:201], v[196:199], off
	v_pk_fma_f32 v[82:83], v[82:83], v[174:175], v[204:205]
	v_pk_fma_f32 v[74:75], v[68:69], v[172:173], v[100:101]
	v_cvt_pk_f16_f32 v196, v187, v195
	v_med3_f32 v187, v88, s95, v247
	v_med3_f32 v195, v89, s95, v247
	v_cvt_pk_f16_f32 v66, v66, v67
	v_med3_f32 v67, v76, s95, v247
	v_med3_f32 v68, v77, s95, v247
	v_pk_fma_f32 v[84:85], v[84:85], v[172:173], v[206:207]
	v_cvt_pk_f16_f32 v197, v187, v195
	v_med3_f32 v187, v82, s95, v247
	v_med3_f32 v195, v83, s95, v247
	v_cvt_pk_f16_f32 v67, v67, v68
	v_med3_f32 v68, v98, s95, v247
	v_med3_f32 v69, v99, s95, v247
	v_cvt_pk_f16_f32 v198, v187, v195
	v_med3_f32 v187, v84, s95, v247
	v_med3_f32 v195, v85, s95, v247
	v_cvt_pk_f16_f32 v68, v68, v69
	v_med3_f32 v69, v74, s95, v247
	v_med3_f32 v70, v75, s95, v247
	v_add_u32_e32 v100, 0x80, v186
	v_cvt_pk_f16_f32 v199, v187, v195
	v_cvt_pk_f16_f32 v69, v69, v70
	v_ashrrev_i32_e32 v101, 31, v100
	global_store_dwordx4 v[200:201], v[196:199], off offset:256
	global_store_dwordx4 v[108:109], v[66:69], off offset:256
	v_add_u32_e32 v104, 0x90, v186
	v_ashrrev_i32_e32 v105, 31, v104
	v_lshlrev_b64 v[66:67], 12, v[100:101]
	v_lshl_add_u64 v[66:67], v[184:185], 0, v[66:67]
	global_load_dwordx4 v[196:199], v[66:67], off offset:16
	global_load_dwordx4 v[200:203], v[66:67], off
	global_load_dwordx4 v[204:207], v[66:67], off offset:528
	global_load_dwordx4 v[208:211], v[66:67], off offset:512
	v_lshlrev_b64 v[66:67], 12, v[104:105]
	v_lshl_add_u64 v[70:71], v[184:185], 0, v[66:67]
	global_load_dwordx4 v[212:215], v[70:71], off offset:16
	global_load_dwordx4 v[216:219], v[70:71], off
	global_load_dwordx4 v[66:69], v[70:71], off offset:528
	s_nop 0
	global_load_dwordx4 v[70:73], v[70:71], off offset:512
	v_lshlrev_b64 v[100:101], 11, v[100:101]
	v_lshlrev_b64 v[104:105], 11, v[104:105]
	s_waitcnt vmcnt(7)
	v_pk_fma_f32 v[58:59], v[58:59], v[170:171], v[196:197]
	s_waitcnt vmcnt(6)
	v_pk_fma_f32 v[62:63], v[62:63], v[178:179], v[200:201]
	v_pk_fma_f32 v[64:65], v[64:65], v[176:177], v[202:203]
	v_med3_f32 v108, v62, s95, v247
	v_med3_f32 v109, v63, s95, v247
	v_cvt_pk_f16_f32 v196, v108, v109
	v_med3_f32 v108, v64, s95, v247
	v_med3_f32 v109, v65, s95, v247
	v_pk_fma_f32 v[60:61], v[60:61], v[168:169], v[198:199]
	v_cvt_pk_f16_f32 v197, v108, v109
	v_med3_f32 v108, v58, s95, v247
	v_med3_f32 v109, v59, s95, v247
	v_cvt_pk_f16_f32 v198, v108, v109
	v_med3_f32 v108, v60, s95, v247
	v_med3_f32 v109, v61, s95, v247
	v_cvt_pk_f16_f32 v199, v108, v109
	v_lshl_add_u64 v[108:109], s[26:27], 0, v[100:101]
	s_waitcnt vmcnt(4)
	v_pk_fma_f32 v[54:55], v[54:55], v[182:183], v[208:209]
	v_lshl_add_u64 v[108:109], v[108:109], 0, v[122:123]
	v_pk_fma_f32 v[56:57], v[56:57], v[180:181], v[210:211]
	v_med3_f32 v112, v54, s95, v247
	v_med3_f32 v113, v55, s95, v247
	global_store_dwordx4 v[108:109], v[196:199], off
	v_pk_fma_f32 v[50:51], v[50:51], v[174:175], v[204:205]
	v_pk_fma_f32 v[52:53], v[52:53], v[172:173], v[206:207]
	v_cvt_pk_f16_f32 v196, v112, v113
	v_med3_f32 v112, v56, s95, v247
	v_med3_f32 v113, v57, s95, v247
	v_cvt_pk_f16_f32 v197, v112, v113
	v_med3_f32 v112, v50, s95, v247
	v_med3_f32 v113, v51, s95, v247
	v_cvt_pk_f16_f32 v198, v112, v113
	v_med3_f32 v112, v52, s95, v247
	v_med3_f32 v113, v53, s95, v247
	v_cvt_pk_f16_f32 v199, v112, v113
	s_waitcnt vmcnt(3)
	v_pk_fma_f32 v[112:113], v[46:47], v[178:179], v[216:217]
	global_store_dwordx4 v[108:109], v[196:199], off offset:256
	v_pk_fma_f32 v[48:49], v[48:49], v[176:177], v[218:219]
	v_pk_fma_f32 v[108:109], v[42:43], v[170:171], v[212:213]
	v_med3_f32 v42, v112, s95, v247
	v_med3_f32 v43, v113, s95, v247
	v_cvt_pk_f16_f32 v196, v42, v43
	v_med3_f32 v42, v48, s95, v247
	v_med3_f32 v43, v49, s95, v247
	v_pk_fma_f32 v[44:45], v[44:45], v[168:169], v[214:215]
	v_cvt_pk_f16_f32 v197, v42, v43
	v_med3_f32 v42, v108, s95, v247
	v_med3_f32 v43, v109, s95, v247
	v_cvt_pk_f16_f32 v198, v42, v43
	v_med3_f32 v42, v44, s95, v247
	v_med3_f32 v43, v45, s95, v247
	v_cvt_pk_f16_f32 v199, v42, v43
	v_lshl_add_u64 v[42:43], s[26:27], 0, v[104:105]
	s_waitcnt vmcnt(2)
	v_pk_fma_f32 v[46:47], v[38:39], v[182:183], v[70:71]
	v_lshl_add_u64 v[200:201], v[42:43], 0, v[122:123]
	v_pk_fma_f32 v[40:41], v[40:41], v[180:181], v[72:73]
	v_pk_fma_f32 v[42:43], v[34:35], v[174:175], v[66:67]
	v_med3_f32 v34, v46, s95, v247
	v_med3_f32 v35, v47, s95, v247
	v_pk_fma_f32 v[38:39], v[36:37], v[172:173], v[68:69]
	v_cvt_pk_f16_f32 v34, v34, v35
	v_med3_f32 v35, v40, s95, v247
	v_med3_f32 v36, v41, s95, v247
	v_cvt_pk_f16_f32 v35, v35, v36
	v_med3_f32 v36, v42, s95, v247
	v_med3_f32 v37, v43, s95, v247
	v_cvt_pk_f16_f32 v36, v36, v37
	v_med3_f32 v37, v38, s95, v247
	v_med3_f32 v66, v39, s95, v247
	v_cvt_pk_f16_f32 v37, v37, v66
	v_add_u32_e32 v66, 0xa0, v186
	v_ashrrev_i32_e32 v67, 31, v66
	global_store_dwordx4 v[200:201], v[196:199], off
	global_store_dwordx4 v[200:201], v[34:37], off offset:256
	v_add_u32_e32 v72, 0xb0, v186
	v_ashrrev_i32_e32 v73, 31, v72
	v_lshlrev_b64 v[34:35], 12, v[66:67]
	v_lshl_add_u64 v[34:35], v[184:185], 0, v[34:35]
	global_load_dwordx4 v[68:71], v[34:35], off offset:16
	global_load_dwordx4 v[196:199], v[34:35], off
	global_load_dwordx4 v[200:203], v[34:35], off offset:528
	global_load_dwordx4 v[204:207], v[34:35], off offset:512
	v_lshlrev_b64 v[34:35], 12, v[72:73]
	v_lshl_add_u64 v[212:213], v[184:185], 0, v[34:35]
	global_load_dwordx4 v[184:187], v[212:213], off offset:16
	global_load_dwordx4 v[208:211], v[212:213], off
	global_load_dwordx4 v[34:37], v[212:213], off offset:528
	s_nop 0
	global_load_dwordx4 v[212:215], v[212:213], off offset:512
	v_lshlrev_b64 v[66:67], 11, v[66:67]
	s_waitcnt vmcnt(7)
	v_pk_fma_f32 v[26:27], v[26:27], v[170:171], v[68:69]
	s_waitcnt vmcnt(6)
	v_pk_fma_f32 v[30:31], v[30:31], v[178:179], v[196:197]
	v_pk_fma_f32 v[32:33], v[32:33], v[176:177], v[198:199]
	v_med3_f32 v68, v30, s95, v247
	v_med3_f32 v69, v31, s95, v247
	v_pk_fma_f32 v[28:29], v[28:29], v[168:169], v[70:71]
	v_cvt_pk_f16_f32 v68, v68, v69
	v_med3_f32 v69, v32, s95, v247
	v_med3_f32 v70, v33, s95, v247
	v_cvt_pk_f16_f32 v69, v69, v70
	v_med3_f32 v70, v26, s95, v247
	v_med3_f32 v71, v27, s95, v247
	v_cvt_pk_f16_f32 v70, v70, v71
	v_med3_f32 v71, v28, s95, v247
	v_med3_f32 v195, v29, s95, v247
	v_lshl_add_u64 v[196:197], s[26:27], 0, v[66:67]
	v_cvt_pk_f16_f32 v71, v71, v195
	v_lshl_add_u64 v[196:197], v[196:197], 0, v[122:123]
	s_waitcnt vmcnt(4)
	v_pk_fma_f32 v[22:23], v[22:23], v[182:183], v[204:205]
	global_store_dwordx4 v[196:197], v[68:71], off
	v_pk_fma_f32 v[24:25], v[24:25], v[180:181], v[206:207]
	v_pk_fma_f32 v[18:19], v[18:19], v[174:175], v[200:201]
	v_med3_f32 v68, v22, s95, v247
	v_med3_f32 v69, v23, s95, v247
	v_cvt_pk_f16_f32 v68, v68, v69
	v_med3_f32 v69, v24, s95, v247
	v_med3_f32 v70, v25, s95, v247
	v_pk_fma_f32 v[20:21], v[20:21], v[172:173], v[202:203]
	v_cvt_pk_f16_f32 v69, v69, v70
	v_med3_f32 v70, v18, s95, v247
	v_med3_f32 v71, v19, s95, v247
	v_cvt_pk_f16_f32 v70, v70, v71
	v_med3_f32 v71, v20, s95, v247
	v_med3_f32 v195, v21, s95, v247
	v_cvt_pk_f16_f32 v71, v71, v195
	s_waitcnt vmcnt(3)
	v_pk_fma_f32 v[178:179], v[14:15], v[178:179], v[208:209]
	global_store_dwordx4 v[196:197], v[68:71], off offset:256
	v_pk_fma_f32 v[176:177], v[16:17], v[176:177], v[210:211]
	v_pk_fma_f32 v[170:171], v[10:11], v[170:171], v[184:185]
	v_lshlrev_b64 v[68:69], 11, v[72:73]
	v_pk_fma_f32 v[72:73], v[12:13], v[168:169], v[186:187]
	v_med3_f32 v10, v178, s95, v247
	v_med3_f32 v11, v179, s95, v247
	s_waitcnt vmcnt(2)
	v_pk_fma_f32 v[168:169], v[6:7], v[182:183], v[212:213]
	v_cvt_pk_f16_f32 v10, v10, v11
	v_med3_f32 v11, v176, s95, v247
	v_med3_f32 v12, v177, s95, v247
	v_pk_fma_f32 v[70:71], v[8:9], v[180:181], v[214:215]
	v_pk_fma_f32 v[34:35], v[2:3], v[174:175], v[34:35]
	v_med3_f32 v2, v168, s95, v247
	v_med3_f32 v3, v169, s95, v247
	v_cvt_pk_f16_f32 v11, v11, v12
	v_med3_f32 v12, v170, s95, v247
	v_med3_f32 v13, v171, s95, v247
	v_pk_fma_f32 v[36:37], v[4:5], v[172:173], v[36:37]
	v_cvt_pk_f16_f32 v2, v2, v3
	v_med3_f32 v3, v70, s95, v247
	v_med3_f32 v4, v71, s95, v247
	v_cvt_pk_f16_f32 v12, v12, v13
	v_med3_f32 v13, v72, s95, v247
	v_med3_f32 v14, v73, s95, v247
	v_cvt_pk_f16_f32 v3, v3, v4
	v_med3_f32 v4, v34, s95, v247
	v_med3_f32 v5, v35, s95, v247
	v_cvt_pk_f16_f32 v13, v13, v14
	v_lshl_add_u64 v[14:15], s[26:27], 0, v[68:69]
	v_cvt_pk_f16_f32 v4, v4, v5
	v_med3_f32 v5, v36, s95, v247
	v_med3_f32 v6, v37, s95, v247
	v_lshl_add_u64 v[14:15], v[14:15], 0, v[122:123]
	v_cvt_pk_f16_f32 v5, v5, v6
	global_store_dwordx4 v[14:15], v[2:5], off offset:256
	global_store_dwordx4 v[14:15], v[10:13], off
	s_nop 0
	v_mul_f32_e32 v2, v161, v161
	v_mul_f32_e32 v3, v129, v129
	v_fmac_f32_e32 v2, v160, v160
	v_fmac_f32_e32 v3, v128, v128
	v_add_f32_e32 v2, v2, v3
	v_mul_f32_e32 v3, v127, v127
	v_mul_f32_e32 v4, v125, v125
	v_fmac_f32_e32 v3, v126, v126
	v_fmac_f32_e32 v4, v124, v124
	v_add_f32_e32 v3, v3, v4
	v_add_f32_e32 v2, v2, v3
	v_mul_f32_e32 v3, v119, v119
	v_mul_f32_e32 v4, v121, v121
	v_fmac_f32_e32 v3, v118, v118
	v_fmac_f32_e32 v4, v120, v120
	v_add_f32_e32 v3, v3, v4
	v_add_f32_e32 v2, v2, v3
	v_mul_f32_e32 v3, v115, v115
	v_mul_f32_e32 v4, v117, v117
	v_fmac_f32_e32 v3, v114, v114
	v_fmac_f32_e32 v4, v116, v116
	v_add_f32_e32 v3, v3, v4
	v_add_f32_e32 v2, v2, v3
	ds_swizzle_b32 v3, v2 offset:swizzle(SWAP,16)
	s_waitcnt lgkmcnt(0)
	v_add_f32_e32 v3, v2, v3
	v_mov_b32_e32 v4, v3
	s_nop 1
	v_permlane32_swap_b32_e32 v3, v4
	v_lshl_add_u32 v2, v193, 4, s86
	s_and_saveexec_b64 s[0:1], vcc
	v_add_f32_e32 v3, v3, v4
	ds_write_b32 v2, v3
	s_or_b64 exec, exec, s[0:1]
	v_mul_f32_e32 v3, v143, v143
	v_mul_f32_e32 v4, v145, v145
	v_fmac_f32_e32 v3, v142, v142
	v_fmac_f32_e32 v4, v144, v144
	v_add_f32_e32 v3, v3, v4
	v_mul_f32_e32 v4, v139, v139
	v_mul_f32_e32 v5, v141, v141
	v_fmac_f32_e32 v4, v138, v138
	v_fmac_f32_e32 v5, v140, v140
	v_add_f32_e32 v4, v4, v5
	v_add_f32_e32 v3, v3, v4
	v_mul_f32_e32 v4, v135, v135
	v_mul_f32_e32 v5, v137, v137
	v_fmac_f32_e32 v4, v134, v134
	v_fmac_f32_e32 v5, v136, v136
	v_add_f32_e32 v4, v4, v5
	v_add_f32_e32 v3, v3, v4
	v_mul_f32_e32 v4, v131, v131
	v_mul_f32_e32 v5, v133, v133
	v_fmac_f32_e32 v4, v130, v130
	v_fmac_f32_e32 v5, v132, v132
	v_add_f32_e32 v4, v4, v5
	v_add_f32_e32 v3, v3, v4
	ds_swizzle_b32 v4, v3 offset:swizzle(SWAP,16)
	s_waitcnt lgkmcnt(0)
	v_add_f32_e32 v3, v3, v4
	v_mov_b32_e32 v4, v3
	s_nop 1
	v_permlane32_swap_b32_e32 v3, v4
	s_and_saveexec_b64 s[0:1], vcc
	v_add_f32_e32 v3, v3, v4
	ds_write_b32 v2, v3 offset:256
	s_or_b64 exec, exec, s[0:1]
	v_mul_f32_e32 v3, v95, v95
	v_mul_f32_e32 v4, v97, v97
	v_fmac_f32_e32 v3, v94, v94
	v_fmac_f32_e32 v4, v96, v96
	v_add_f32_e32 v3, v3, v4
	v_mul_f32_e32 v4, v91, v91
	v_mul_f32_e32 v5, v93, v93
	v_fmac_f32_e32 v4, v90, v90
	v_fmac_f32_e32 v5, v92, v92
	v_add_f32_e32 v4, v4, v5
	v_add_f32_e32 v3, v3, v4
	v_mul_f32_e32 v4, v87, v87
	v_mul_f32_e32 v5, v89, v89
	v_fmac_f32_e32 v4, v86, v86
	v_fmac_f32_e32 v5, v88, v88
	v_add_f32_e32 v4, v4, v5
	v_add_f32_e32 v3, v3, v4
	v_mul_f32_e32 v4, v83, v83
	v_mul_f32_e32 v5, v85, v85
	v_fmac_f32_e32 v4, v82, v82
	v_fmac_f32_e32 v5, v84, v84
	v_add_f32_e32 v4, v4, v5
	v_add_f32_e32 v3, v3, v4
	ds_swizzle_b32 v4, v3 offset:swizzle(SWAP,16)
	s_waitcnt lgkmcnt(0)
	v_add_f32_e32 v3, v3, v4
	v_mov_b32_e32 v4, v3
	s_nop 1
	v_permlane32_swap_b32_e32 v3, v4
	s_and_saveexec_b64 s[0:1], vcc
	v_add_f32_e32 v3, v3, v4
	ds_write_b32 v2, v3 offset:512
	s_or_b64 exec, exec, s[0:1]
	v_mul_f32_e32 v3, v111, v111
	v_mul_f32_e32 v4, v81, v81
	v_fmac_f32_e32 v3, v110, v110
	v_fmac_f32_e32 v4, v80, v80
	v_add_f32_e32 v3, v3, v4
	v_mul_f32_e32 v4, v107, v107
	v_mul_f32_e32 v5, v79, v79
	v_fmac_f32_e32 v4, v106, v106
	v_fmac_f32_e32 v5, v78, v78
	v_add_f32_e32 v4, v4, v5
	v_add_f32_e32 v3, v3, v4
	v_mul_f32_e32 v4, v103, v103
	v_mul_f32_e32 v5, v77, v77
	v_fmac_f32_e32 v4, v102, v102
	v_fmac_f32_e32 v5, v76, v76
	v_add_f32_e32 v4, v4, v5
	v_add_f32_e32 v3, v3, v4
	v_mul_f32_e32 v4, v99, v99
	v_mul_f32_e32 v5, v75, v75
	v_fmac_f32_e32 v4, v98, v98
	v_fmac_f32_e32 v5, v74, v74
	v_add_f32_e32 v4, v4, v5
	v_add_f32_e32 v3, v3, v4
	ds_swizzle_b32 v4, v3 offset:swizzle(SWAP,16)
	s_waitcnt lgkmcnt(0)
	v_add_f32_e32 v3, v3, v4
	v_mov_b32_e32 v4, v3
	s_nop 1
	v_permlane32_swap_b32_e32 v3, v4
	s_and_saveexec_b64 s[0:1], vcc
	v_add_f32_e32 v3, v3, v4
	ds_write_b32 v2, v3 offset:768
	s_or_b64 exec, exec, s[0:1]
	v_mul_f32_e32 v3, v63, v63
	v_mul_f32_e32 v4, v65, v65
	v_fmac_f32_e32 v3, v62, v62
	v_fmac_f32_e32 v4, v64, v64
	v_add_f32_e32 v3, v3, v4
	v_mul_f32_e32 v4, v59, v59
	v_mul_f32_e32 v5, v61, v61
	v_fmac_f32_e32 v4, v58, v58
	v_fmac_f32_e32 v5, v60, v60
	v_add_f32_e32 v4, v4, v5
	v_add_f32_e32 v3, v3, v4
	v_mul_f32_e32 v4, v55, v55
	v_mul_f32_e32 v5, v57, v57
	v_fmac_f32_e32 v4, v54, v54
	v_fmac_f32_e32 v5, v56, v56
	v_add_f32_e32 v4, v4, v5
	v_add_f32_e32 v3, v3, v4
	v_mul_f32_e32 v4, v51, v51
	v_mul_f32_e32 v5, v53, v53
	v_fmac_f32_e32 v4, v50, v50
	v_fmac_f32_e32 v5, v52, v52
	v_add_f32_e32 v4, v4, v5
	v_add_f32_e32 v3, v3, v4
	ds_swizzle_b32 v4, v3 offset:swizzle(SWAP,16)
	s_waitcnt lgkmcnt(0)
	v_add_f32_e32 v3, v3, v4
	v_mov_b32_e32 v4, v3
	s_nop 1
	v_permlane32_swap_b32_e32 v3, v4
	s_and_saveexec_b64 s[0:1], vcc
	v_add_f32_e32 v3, v3, v4
	ds_write_b32 v2, v3 offset:2048
	s_or_b64 exec, exec, s[0:1]
	v_mul_f32_e32 v3, v113, v113
	v_mul_f32_e32 v4, v49, v49
	v_fmac_f32_e32 v3, v112, v112
	v_fmac_f32_e32 v4, v48, v48
	v_add_f32_e32 v3, v3, v4
	v_mul_f32_e32 v4, v109, v109
	v_mul_f32_e32 v5, v45, v45
	v_fmac_f32_e32 v4, v108, v108
	v_fmac_f32_e32 v5, v44, v44
	v_add_f32_e32 v4, v4, v5
	v_add_f32_e32 v3, v3, v4
	v_mul_f32_e32 v4, v47, v47
	v_mul_f32_e32 v5, v41, v41
	v_fmac_f32_e32 v4, v46, v46
	v_fmac_f32_e32 v5, v40, v40
	v_add_f32_e32 v4, v4, v5
	v_add_f32_e32 v3, v3, v4
	v_mul_f32_e32 v4, v43, v43
	v_mul_f32_e32 v5, v39, v39
	v_fmac_f32_e32 v4, v42, v42
	v_fmac_f32_e32 v5, v38, v38
	v_add_f32_e32 v4, v4, v5
	v_add_f32_e32 v3, v3, v4
	ds_swizzle_b32 v4, v3 offset:swizzle(SWAP,16)
	s_waitcnt lgkmcnt(0)
	v_add_f32_e32 v3, v3, v4
	v_mov_b32_e32 v4, v3
	s_nop 1
	v_permlane32_swap_b32_e32 v3, v4
	s_and_saveexec_b64 s[0:1], vcc
	v_add_f32_e32 v3, v3, v4
	ds_write_b32 v2, v3 offset:2304
	s_or_b64 exec, exec, s[0:1]
	v_mul_f32_e32 v3, v31, v31
	v_mul_f32_e32 v4, v33, v33
	v_fmac_f32_e32 v3, v30, v30
	v_fmac_f32_e32 v4, v32, v32
	v_add_f32_e32 v3, v3, v4
	v_mul_f32_e32 v4, v27, v27
	v_mul_f32_e32 v5, v29, v29
	v_fmac_f32_e32 v4, v26, v26
	v_fmac_f32_e32 v5, v28, v28
	v_add_f32_e32 v4, v4, v5
	v_add_f32_e32 v3, v3, v4
	v_mul_f32_e32 v4, v23, v23
	v_mul_f32_e32 v5, v25, v25
	v_fmac_f32_e32 v4, v22, v22
	v_fmac_f32_e32 v5, v24, v24
	v_add_f32_e32 v4, v4, v5
	v_add_f32_e32 v3, v3, v4
	v_mul_f32_e32 v4, v19, v19
	v_mul_f32_e32 v5, v21, v21
	v_fmac_f32_e32 v4, v18, v18
	v_fmac_f32_e32 v5, v20, v20
	v_add_f32_e32 v4, v4, v5
	v_add_f32_e32 v3, v3, v4
	ds_swizzle_b32 v4, v3 offset:swizzle(SWAP,16)
	s_waitcnt lgkmcnt(0)
	v_add_f32_e32 v3, v3, v4
	v_mov_b32_e32 v4, v3
	s_nop 1
	v_permlane32_swap_b32_e32 v3, v4
	s_and_saveexec_b64 s[0:1], vcc
	v_add_f32_e32 v3, v3, v4
	ds_write_b32 v2, v3 offset:2560
	s_or_b64 exec, exec, s[0:1]
	v_mul_f32_e32 v3, v179, v179
	v_mul_f32_e32 v4, v177, v177
	v_fmac_f32_e32 v3, v178, v178
	v_fmac_f32_e32 v4, v176, v176
	v_add_f32_e32 v3, v3, v4
	v_mul_f32_e32 v4, v171, v171
	v_mul_f32_e32 v5, v73, v73
	v_fmac_f32_e32 v4, v170, v170
	v_fmac_f32_e32 v5, v72, v72
	v_add_f32_e32 v4, v4, v5
	v_add_f32_e32 v3, v3, v4
	v_mul_f32_e32 v4, v169, v169
	v_mul_f32_e32 v5, v71, v71
	v_fmac_f32_e32 v4, v168, v168
	v_fmac_f32_e32 v5, v70, v70
	v_add_f32_e32 v4, v4, v5
	v_add_f32_e32 v3, v3, v4
	v_mul_f32_e32 v4, v35, v35
	v_mul_f32_e32 v5, v37, v37
	v_fmac_f32_e32 v4, v34, v34
	v_fmac_f32_e32 v5, v36, v36
	v_add_f32_e32 v4, v4, v5
	v_add_f32_e32 v3, v3, v4
	ds_swizzle_b32 v4, v3 offset:swizzle(SWAP,16)
	s_waitcnt lgkmcnt(0)
	v_add_f32_e32 v3, v3, v4
	v_mov_b32_e32 v4, v3
	s_nop 1
	v_permlane32_swap_b32_e32 v3, v4
	s_and_saveexec_b64 s[0:1], vcc
	v_add_f32_e32 v3, v3, v4
	ds_write_b32 v2, v3 offset:2816
	s_or_b64 exec, exec, s[0:1]
	v_lshl_add_u32 v5, v194, 4, v193
	s_waitcnt lgkmcnt(0)
	s_barrier
	v_and_or_b32 v4, v5, 31, s75
	v_add_u32_e32 v2, s2, v4
	v_cmp_gt_i32_e64 s[6:7], 32, v5
	v_ashrrev_i32_e32 v3, 31, v2
	s_and_saveexec_b64 s[0:1], s[6:7]
	s_cbranch_execz .LBB0_613
	v_lshl_add_u32 v6, v4, 4, 0
	v_add_u32_e32 v6, 0x20400, v6
	ds_read_b128 v[6:9], v6
	s_ashr_i32 s53, s52, 31
	s_waitcnt lgkmcnt(0)
	v_mov_b32_e32 v10, v7
	v_mov_b32_e32 v11, v8
	v_mov_b32_e32 v7, v9
	v_pk_add_f32 v[6:7], v[10:11], v[6:7]
	v_lshl_add_u64 v[8:9], v[2:3], 4, s[8:9]
	v_pk_add_f32 v[6:7], v[6:7], v[6:7] op_sel:[0,1] op_sel_hi:[1,0]
	v_lshl_add_u64 v[8:9], s[52:53], 2, v[8:9]
	global_store_dword v[8:9], v6, off sc1
